# RWKV prompt scan: y partial sums of 16 steps kept per lane and reduce-scattered together (was a 16-lane all-reduce per step)
# speedup vs baseline: 1.0766x; 1.0082x over previous
.Lrwq_noq0_a:
	s_add_u32 s0, s0, 0x5200
	s_addc_u32 s1, s1, 0
	global_load_short_d16_hi v100, v175, s[0:1] offset:-2048
	global_load_short_d16_hi v108, v175, s[0:1]
	global_load_short_d16_hi v116, v175, s[0:1] offset:2048
	s_add_u32 s0, s0, 0x5200
	s_addc_u32 s1, s1, 0
	global_load_short_d16_hi v101, v175, s[0:1] offset:-2048
	global_load_short_d16_hi v109, v175, s[0:1]
	global_load_short_d16_hi v117, v175, s[0:1] offset:2048
	s_add_u32 s0, s0, 0x5200
	s_addc_u32 s1, s1, 0
	global_load_short_d16_hi v102, v175, s[0:1] offset:-2048
	global_load_short_d16_hi v110, v175, s[0:1]
	global_load_short_d16_hi v118, v175, s[0:1] offset:2048
	s_add_u32 s0, s0, 0x5200
	s_addc_u32 s1, s1, 0
	global_load_short_d16_hi v103, v175, s[0:1] offset:-2048
	global_load_short_d16_hi v111, v175, s[0:1]
	global_load_short_d16_hi v119, v175, s[0:1] offset:2048
	s_add_u32 s0, s0, 0x5200
	s_addc_u32 s1, s1, 0
	global_load_short_d16_hi v104, v175, s[0:1] offset:-2048
	global_load_short_d16_hi v112, v175, s[0:1]
	global_load_short_d16_hi v120, v175, s[0:1] offset:2048
	s_add_u32 s0, s0, 0x5200
	s_addc_u32 s1, s1, 0
	global_load_short_d16_hi v105, v175, s[0:1] offset:-2048
	global_load_short_d16_hi v113, v175, s[0:1]
	global_load_short_d16_hi v121, v175, s[0:1] offset:2048
	s_add_u32 s0, s0, 0x5200
	s_addc_u32 s1, s1, 0
	global_load_short_d16_hi v106, v175, s[0:1] offset:-2048
	global_load_short_d16_hi v114, v175, s[0:1]
	global_load_short_d16_hi v122, v175, s[0:1] offset:2048
	s_add_u32 s0, s0, 0x5200
	s_addc_u32 s1, s1, 0
	global_load_short_d16_hi v107, v175, s[0:1] offset:-2048
	global_load_short_d16_hi v115, v175, s[0:1]
	global_load_short_d16_hi v123, v175, s[0:1] offset:2048
	s_add_u32 s0, s100, 0x0
	s_addc_u32 s1, s101, 0
	global_load_short_d16_hi v124, v175, s[0:1]
	global_load_short_d16_hi v125, v175, s[0:1] offset:2048
	s_add_u32 s0, s58, 0x0
	s_addc_u32 s1, s59, 0
	global_load_short_d16_hi v132, v175, s[0:1]
	global_load_short_d16_hi v133, v175, s[0:1] offset:2048
	s_add_u32 s0, s100, 0x1000
	s_addc_u32 s1, s101, 0
	global_load_short_d16_hi v126, v175, s[0:1]
	global_load_short_d16_hi v127, v175, s[0:1] offset:2048
	s_add_u32 s0, s58, 0x1000
	s_addc_u32 s1, s59, 0
	global_load_short_d16_hi v134, v175, s[0:1]
	global_load_short_d16_hi v135, v175, s[0:1] offset:2048
	s_add_u32 s0, s100, 0x2000
	s_addc_u32 s1, s101, 0
	global_load_short_d16_hi v128, v175, s[0:1]
	global_load_short_d16_hi v129, v175, s[0:1] offset:2048
	s_add_u32 s0, s58, 0x2000
	s_addc_u32 s1, s59, 0
	global_load_short_d16_hi v136, v175, s[0:1]
	global_load_short_d16_hi v137, v175, s[0:1] offset:2048
	s_add_u32 s0, s100, 0x3000
	s_addc_u32 s1, s101, 0
	global_load_short_d16_hi v130, v175, s[0:1]
	global_load_short_d16_hi v131, v175, s[0:1] offset:2048
	s_add_u32 s0, s58, 0x3000
	s_addc_u32 s1, s59, 0
	global_load_short_d16_hi v138, v175, s[0:1]
	global_load_short_d16_hi v139, v175, s[0:1] offset:2048
	global_load_dwordx4 v[140:143], v77, s[60:61] offset:-4
	global_load_dwordx4 v[144:147], v77, s[60:61] offset:252
	global_load_dwordx4 v[148:151], v77, s[60:61] offset:508
	global_load_dwordx4 v[152:155], v77, s[60:61] offset:764
	global_load_dwordx4 v[156:159], v77, s[60:61] offset:1020
	global_load_dwordx4 v[160:163], v77, s[60:61] offset:1276
	global_load_dwordx4 v[164:167], v77, s[60:61] offset:1532
	global_load_dwordx4 v[168:171], v77, s[60:61] offset:1788
	s_add_u32 s98, s98, 0xa4000
	s_addc_u32 s99, s99, 0
	s_add_u32 s100, s100, 0x10000
	s_addc_u32 s101, s101, 0
	s_add_u32 s58, s58, 0x10000
	s_addc_u32 s59, s59, 0
	s_add_u32 s60, s60, 0x2000
	s_addc_u32 s61, s61, 0
	s_waitcnt vmcnt(0)
	v_sub_f32_e32 v221, 1.0, v200
	s_mov_b32 s0, 0
	s_waitcnt vmcnt(0)
	v_add_u32_e32 v222, s0, v224
	v_add_u32_e32 v223, s0, v225
	v_mul_f32_e32 v204, 0xbfb8aa3b, v124
	v_mul_f32_e32 v205, 0x3fb8aa3b, v124
	v_sub_f32_e32 v208, v172, v100
	v_exp_f32_e32 v211, v204
	v_exp_f32_e32 v212, v205
	v_sub_f32_e32 v209, v173, v108
	v_sub_f32_e32 v210, v174, v116
	v_fma_f32 v208, v196, v208, v100
	v_fma_f32 v209, v197, v209, v108
	v_fma_f32 v210, v198, v210, v116
	v_mul_f32_e32 v213, v209, v199
	v_fma_f32 v214, v132, v200, v221
	v_mul_f32_e32 v213, v213, v141
	v_mul_f32_e32 v215, v209, v214
	v_mul_f32_e32 v217, -1.0, v213
	v_mul_f32_e32 v216, v213, v132
	v_mul_f32_e32 v218, v211, v208
	v_fmac_f32_e32 v218, v142, v217
	ds_write2st64_b32 v222, v217, v218 offset0:0 offset1:1
	v_mul_f32_e32 v219, v216, v212
	v_mul_f32_e32 v220, v215, v212
	ds_write2st64_b32 v222, v211, v219 offset0:2 offset1:3
	ds_write_b32 v222, v220 offset:1024
	ds_write_b32 v223, v210 offset:0
	v_mul_f32_e32 v214, 0x3d800000, v143
	ds_write_b32 v223, v214 offset:8
	v_mul_f32_e32 v204, 0xbfb8aa3b, v125
	v_mul_f32_e32 v205, 0x3fb8aa3b, v125
	v_sub_f32_e32 v208, v100, v101
	v_exp_f32_e32 v206, v204
	v_exp_f32_e32 v207, v205
	v_sub_f32_e32 v209, v108, v109
	v_sub_f32_e32 v210, v116, v117
	v_fma_f32 v208, v196, v208, v101
	v_fma_f32 v209, v197, v209, v109
	v_fma_f32 v210, v198, v210, v117
	v_mul_f32_e32 v213, v209, v199
	v_fma_f32 v214, v133, v200, v221
	v_mul_f32_e32 v213, v213, v145
	v_mul_f32_e32 v215, v209, v214
	v_mul_f32_e64 v217, -v213, v211
	v_mul_f32_e32 v211, v211, v206
	v_mul_f32_e32 v212, v212, v207
	v_mul_f32_e32 v216, v213, v133
	v_mul_f32_e32 v218, v211, v208
	v_fmac_f32_e32 v218, v146, v217
	ds_write2st64_b32 v222, v217, v218 offset0:7 offset1:8
	v_mul_f32_e32 v219, v216, v212
	v_mul_f32_e32 v220, v215, v212
	ds_write2st64_b32 v222, v211, v219 offset0:9 offset1:10
	ds_write_b32 v222, v220 offset:2816
	ds_write_b32 v223, v210 offset:1792
	v_mul_f32_e32 v214, 0x3d800000, v147
	ds_write_b32 v223, v214 offset:1800
	v_mul_f32_e32 v204, 0xbfb8aa3b, v126
	v_mul_f32_e32 v205, 0x3fb8aa3b, v126
	v_sub_f32_e32 v208, v101, v102
	v_exp_f32_e32 v206, v204
	v_exp_f32_e32 v207, v205
	v_sub_f32_e32 v209, v109, v110
	v_sub_f32_e32 v210, v117, v118
	v_fma_f32 v208, v196, v208, v102
	v_fma_f32 v209, v197, v209, v110
	v_fma_f32 v210, v198, v210, v118
	v_mul_f32_e32 v213, v209, v199
	v_fma_f32 v214, v134, v200, v221
	v_mul_f32_e32 v213, v213, v149
	v_mul_f32_e32 v215, v209, v214
	v_mul_f32_e64 v217, -v213, v211
	v_mul_f32_e32 v211, v211, v206
	v_mul_f32_e32 v212, v212, v207
	v_mul_f32_e32 v216, v213, v134
	v_mul_f32_e32 v218, v211, v208
	v_fmac_f32_e32 v218, v150, v217
	ds_write2st64_b32 v222, v217, v218 offset0:14 offset1:15
	v_mul_f32_e32 v219, v216, v212
	v_mul_f32_e32 v220, v215, v212
	ds_write2st64_b32 v222, v211, v219 offset0:16 offset1:17
	ds_write_b32 v222, v220 offset:4608
	ds_write_b32 v223, v210 offset:3584
	v_mul_f32_e32 v214, 0x3d800000, v151
	ds_write_b32 v223, v214 offset:3592
	v_mul_f32_e32 v204, 0xbfb8aa3b, v127
	v_mul_f32_e32 v205, 0x3fb8aa3b, v127
	v_sub_f32_e32 v208, v102, v103
	v_exp_f32_e32 v206, v204
	v_exp_f32_e32 v207, v205
	v_sub_f32_e32 v209, v110, v111
	v_sub_f32_e32 v210, v118, v119
	v_fma_f32 v208, v196, v208, v103
	v_fma_f32 v209, v197, v209, v111
	v_fma_f32 v210, v198, v210, v119
	v_mul_f32_e32 v213, v209, v199
	v_fma_f32 v214, v135, v200, v221
	v_mul_f32_e32 v213, v213, v153
	v_mul_f32_e32 v215, v209, v214
	v_mul_f32_e64 v217, -v213, v211
	v_mul_f32_e32 v211, v211, v206
	v_mul_f32_e32 v212, v212, v207
	v_mul_f32_e32 v216, v213, v135
	v_mul_f32_e32 v218, v211, v208
	v_fmac_f32_e32 v218, v154, v217
	ds_write2st64_b32 v222, v217, v218 offset0:21 offset1:22
	v_mul_f32_e32 v219, v216, v212
	v_mul_f32_e32 v220, v215, v212
	ds_write2st64_b32 v222, v211, v219 offset0:23 offset1:24
	ds_write_b32 v222, v220 offset:6400
	ds_write_b32 v223, v210 offset:5376
	v_mul_f32_e32 v214, 0x3d800000, v155
	ds_write_b32 v223, v214 offset:5384
	v_mul_f32_e32 v204, 0xbfb8aa3b, v128
	v_mul_f32_e32 v205, 0x3fb8aa3b, v128
	v_sub_f32_e32 v208, v103, v104
	v_exp_f32_e32 v206, v204
	v_exp_f32_e32 v207, v205
	v_sub_f32_e32 v209, v111, v112
	v_sub_f32_e32 v210, v119, v120
	v_fma_f32 v208, v196, v208, v104
	v_fma_f32 v209, v197, v209, v112
	v_fma_f32 v210, v198, v210, v120
	v_mul_f32_e32 v213, v209, v199
	v_fma_f32 v214, v136, v200, v221
	v_mul_f32_e32 v213, v213, v157
	v_mul_f32_e32 v215, v209, v214
	v_mul_f32_e64 v217, -v213, v211
	v_mul_f32_e32 v211, v211, v206
	v_mul_f32_e32 v212, v212, v207
	v_mul_f32_e32 v216, v213, v136
	v_mul_f32_e32 v218, v211, v208
	v_fmac_f32_e32 v218, v158, v217
	ds_write2st64_b32 v222, v217, v218 offset0:28 offset1:29
	v_mul_f32_e32 v219, v216, v212
	v_mul_f32_e32 v220, v215, v212
	ds_write2st64_b32 v222, v211, v219 offset0:30 offset1:31
	ds_write_b32 v222, v220 offset:8192
	ds_write_b32 v223, v210 offset:7168
	v_mul_f32_e32 v214, 0x3d800000, v159
	ds_write_b32 v223, v214 offset:7176
	v_mul_f32_e32 v204, 0xbfb8aa3b, v129
	v_mul_f32_e32 v205, 0x3fb8aa3b, v129
	v_sub_f32_e32 v208, v104, v105
	v_exp_f32_e32 v206, v204
	v_exp_f32_e32 v207, v205
	v_sub_f32_e32 v209, v112, v113
	v_sub_f32_e32 v210, v120, v121
	v_fma_f32 v208, v196, v208, v105
	v_fma_f32 v209, v197, v209, v113
	v_fma_f32 v210, v198, v210, v121
	v_mul_f32_e32 v213, v209, v199
	v_fma_f32 v214, v137, v200, v221
	v_mul_f32_e32 v213, v213, v161
	v_mul_f32_e32 v215, v209, v214
	v_mul_f32_e64 v217, -v213, v211
	v_mul_f32_e32 v211, v211, v206
	v_mul_f32_e32 v212, v212, v207
	v_mul_f32_e32 v216, v213, v137
	v_mul_f32_e32 v218, v211, v208
	v_fmac_f32_e32 v218, v162, v217
	ds_write2st64_b32 v222, v217, v218 offset0:35 offset1:36
	v_mul_f32_e32 v219, v216, v212
	v_mul_f32_e32 v220, v215, v212
	ds_write2st64_b32 v222, v211, v219 offset0:37 offset1:38
	ds_write_b32 v222, v220 offset:9984
	ds_write_b32 v223, v210 offset:8960
	v_mul_f32_e32 v214, 0x3d800000, v163
	ds_write_b32 v223, v214 offset:8968
	v_mul_f32_e32 v204, 0xbfb8aa3b, v130
	v_mul_f32_e32 v205, 0x3fb8aa3b, v130
	v_sub_f32_e32 v208, v105, v106
	v_exp_f32_e32 v206, v204
	v_exp_f32_e32 v207, v205
	v_sub_f32_e32 v209, v113, v114
	v_sub_f32_e32 v210, v121, v122
	v_fma_f32 v208, v196, v208, v106
	v_fma_f32 v209, v197, v209, v114
	v_fma_f32 v210, v198, v210, v122
	v_mul_f32_e32 v213, v209, v199
	v_fma_f32 v214, v138, v200, v221
	v_mul_f32_e32 v213, v213, v165
	v_mul_f32_e32 v215, v209, v214
	v_mul_f32_e64 v217, -v213, v211
	v_mul_f32_e32 v211, v211, v206
	v_mul_f32_e32 v212, v212, v207
	v_mul_f32_e32 v216, v213, v138
	v_mul_f32_e32 v218, v211, v208
	v_fmac_f32_e32 v218, v166, v217
	ds_write2st64_b32 v222, v217, v218 offset0:42 offset1:43
	v_mul_f32_e32 v219, v216, v212
	v_mul_f32_e32 v220, v215, v212
	ds_write2st64_b32 v222, v211, v219 offset0:44 offset1:45
	ds_write_b32 v222, v220 offset:11776
	ds_write_b32 v223, v210 offset:10752
	v_mul_f32_e32 v214, 0x3d800000, v167
	ds_write_b32 v223, v214 offset:10760
	v_mul_f32_e32 v204, 0xbfb8aa3b, v131
	v_mul_f32_e32 v205, 0x3fb8aa3b, v131
	v_sub_f32_e32 v208, v106, v107
	v_exp_f32_e32 v206, v204
	v_exp_f32_e32 v207, v205
	v_sub_f32_e32 v209, v114, v115
	v_sub_f32_e32 v210, v122, v123
	v_fma_f32 v208, v196, v208, v107
	v_fma_f32 v209, v197, v209, v115
	v_fma_f32 v210, v198, v210, v123
	v_mul_f32_e32 v213, v209, v199
	v_fma_f32 v214, v139, v200, v221
	v_mul_f32_e32 v213, v213, v169
	v_mul_f32_e32 v215, v209, v214
	v_mul_f32_e64 v217, -v213, v211
	v_mul_f32_e32 v211, v211, v206
	v_mul_f32_e32 v212, v212, v207
	v_mul_f32_e32 v216, v213, v139
	v_mul_f32_e32 v218, v211, v208
	v_fmac_f32_e32 v218, v170, v217
	ds_write2st64_b32 v222, v217, v218 offset0:49 offset1:50
	v_mul_f32_e32 v219, v216, v212
	v_mul_f32_e32 v220, v215, v212
	ds_write2st64_b32 v222, v211, v219 offset0:51 offset1:52
	ds_write_b32 v222, v220 offset:13568
	ds_write_b32 v223, v210 offset:12544
	v_mul_f32_e32 v214, 0x3d800000, v171
	ds_write_b32 v223, v214 offset:12552
	s_sub_u32 s0, s98, 0x5200
	s_subb_u32 s1, s99, 0
	global_load_short_d16_hi v172, v175, s[0:1] offset:-2048
	global_load_short_d16_hi v173, v175, s[0:1]
	global_load_short_d16_hi v174, v175, s[0:1] offset:2048
	s_add_u32 s0, s0, 0x5200
	s_addc_u32 s1, s1, 0
	global_load_short_d16_hi v100, v175, s[0:1] offset:-2048
	global_load_short_d16_hi v108, v175, s[0:1]
	global_load_short_d16_hi v116, v175, s[0:1] offset:2048
	s_add_u32 s0, s0, 0x5200
	s_addc_u32 s1, s1, 0
	global_load_short_d16_hi v101, v175, s[0:1] offset:-2048
	global_load_short_d16_hi v109, v175, s[0:1]
	global_load_short_d16_hi v117, v175, s[0:1] offset:2048
	s_add_u32 s0, s0, 0x5200
	s_addc_u32 s1, s1, 0
	global_load_short_d16_hi v102, v175, s[0:1] offset:-2048
	global_load_short_d16_hi v110, v175, s[0:1]
	global_load_short_d16_hi v118, v175, s[0:1] offset:2048
	s_add_u32 s0, s0, 0x5200
	s_addc_u32 s1, s1, 0
	global_load_short_d16_hi v103, v175, s[0:1] offset:-2048
	global_load_short_d16_hi v111, v175, s[0:1]
	global_load_short_d16_hi v119, v175, s[0:1] offset:2048
	s_add_u32 s0, s0, 0x5200
	s_addc_u32 s1, s1, 0
	global_load_short_d16_hi v104, v175, s[0:1] offset:-2048
	global_load_short_d16_hi v112, v175, s[0:1]
	global_load_short_d16_hi v120, v175, s[0:1] offset:2048
	s_add_u32 s0, s0, 0x5200
	s_addc_u32 s1, s1, 0
	global_load_short_d16_hi v105, v175, s[0:1] offset:-2048
	global_load_short_d16_hi v113, v175, s[0:1]
	global_load_short_d16_hi v121, v175, s[0:1] offset:2048
	s_add_u32 s0, s0, 0x5200
	s_addc_u32 s1, s1, 0
	global_load_short_d16_hi v106, v175, s[0:1] offset:-2048
	global_load_short_d16_hi v114, v175, s[0:1]
	global_load_short_d16_hi v122, v175, s[0:1] offset:2048
	s_add_u32 s0, s0, 0x5200
	s_addc_u32 s1, s1, 0
	global_load_short_d16_hi v107, v175, s[0:1] offset:-2048
	global_load_short_d16_hi v115, v175, s[0:1]
	global_load_short_d16_hi v123, v175, s[0:1] offset:2048
	s_add_u32 s0, s100, 0x0
	s_addc_u32 s1, s101, 0
	global_load_short_d16_hi v124, v175, s[0:1]
	global_load_short_d16_hi v125, v175, s[0:1] offset:2048
	s_add_u32 s0, s58, 0x0
	s_addc_u32 s1, s59, 0
	global_load_short_d16_hi v132, v175, s[0:1]
	global_load_short_d16_hi v133, v175, s[0:1] offset:2048
	s_add_u32 s0, s100, 0x1000
	s_addc_u32 s1, s101, 0
	global_load_short_d16_hi v126, v175, s[0:1]
	global_load_short_d16_hi v127, v175, s[0:1] offset:2048
	s_add_u32 s0, s58, 0x1000
	s_addc_u32 s1, s59, 0
	global_load_short_d16_hi v134, v175, s[0:1]
	global_load_short_d16_hi v135, v175, s[0:1] offset:2048
	s_add_u32 s0, s100, 0x2000
	s_addc_u32 s1, s101, 0
	global_load_short_d16_hi v128, v175, s[0:1]
	global_load_short_d16_hi v129, v175, s[0:1] offset:2048
	s_add_u32 s0, s58, 0x2000
	s_addc_u32 s1, s59, 0
	global_load_short_d16_hi v136, v175, s[0:1]
	global_load_short_d16_hi v137, v175, s[0:1] offset:2048
	s_add_u32 s0, s100, 0x3000
	s_addc_u32 s1, s101, 0
	global_load_short_d16_hi v130, v175, s[0:1]
	global_load_short_d16_hi v131, v175, s[0:1] offset:2048
	s_add_u32 s0, s58, 0x3000
	s_addc_u32 s1, s59, 0
	global_load_short_d16_hi v138, v175, s[0:1]
	global_load_short_d16_hi v139, v175, s[0:1] offset:2048
	global_load_dwordx4 v[140:143], v77, s[60:61] offset:-4
	global_load_dwordx4 v[144:147], v77, s[60:61] offset:252
	global_load_dwordx4 v[148:151], v77, s[60:61] offset:508
	global_load_dwordx4 v[152:155], v77, s[60:61] offset:764
	global_load_dwordx4 v[156:159], v77, s[60:61] offset:1020
	global_load_dwordx4 v[160:163], v77, s[60:61] offset:1276
	global_load_dwordx4 v[164:167], v77, s[60:61] offset:1532
	global_load_dwordx4 v[168:171], v77, s[60:61] offset:1788
	s_add_u32 s98, s98, 0xa4000
	s_addc_u32 s99, s99, 0
	s_add_u32 s100, s100, 0x10000
	s_addc_u32 s101, s101, 0
	s_add_u32 s58, s58, 0x10000
	s_addc_u32 s59, s59, 0
	s_add_u32 s60, s60, 0x2000
	s_addc_u32 s61, s61, 0
	s_cmp_eq_u32 s48, 0x100
	s_cbranch_scc0 .Lya_pre_skip
	v_add_u32_e32 v233, -4, v179
	v_lshl_add_u32 v233, v233, 6, v1
	v_mov_b32_e32 v246, 0x20070
	ds_read_b64 v[242:243], v246
	v_lshlrev_b32_e32 v230, 5, v233
	v_lshlrev_b32_e32 v233, 4, v233
	s_waitcnt lgkmcnt(0)
	v_readfirstlane_b32 s52, v242
	v_readfirstlane_b32 s53, v243
	s_nop 4
	global_load_dwordx4 v[234:237], v230, s[52:53]
	global_load_dwordx4 v[238:241], v230, s[52:53] offset:16
	s_mov_b32 s55, 0
	s_lshl_b32 s54, s55, 9
	s_add_u32 s54, s54, s2
	s_mul_i32 s52, s54, 0x5200
	s_add_u32 s52, s20, s52
	s_addc_u32 s53, s21, 0
	global_load_dwordx4 v[242:245], v233, s[52:53]
	s_add_u32 s52, s52, 0x520000
	s_addc_u32 s53, s53, 0
	global_load_dwordx4 v[226:229], v233, s[52:53]
	s_lshl_b32 s52, s54, 4
	s_lshl_b32 s53, s33, 2
	s_add_u32 s52, s52, s53
	s_add_u32 s52, s46, s52
	s_addc_u32 s53, s47, 0
	global_load_dword v247, v77, s[52:53]
	s_add_u32 s52, s52, 0x1000
	s_addc_u32 s53, s53, 0
	global_load_dword v248, v77, s[52:53]

.LBB0_1348:
	s_and_saveexec_b64 s[0:1], s[16:17]
	s_xor_b64 s[56:57], exec, s[0:1]
	s_cbranch_execz .LBB0_1368
	s_cmp_eq_u32 s30, 63
	s_cbranch_scc1 .LBB0_1368
	s_andn2_b32 s0, 1, s30
	s_mul_i32 s0, s0, 0xe000
	s_waitcnt vmcnt(0)
	v_add_u32_e32 v222, s0, v224
	v_add_u32_e32 v223, s0, v225
	v_mul_f32_e32 v204, 0xbfb8aa3b, v124
	v_mul_f32_e32 v205, 0x3fb8aa3b, v124
	v_sub_f32_e32 v208, v172, v100
	v_exp_f32_e32 v211, v204
	v_exp_f32_e32 v212, v205
	v_sub_f32_e32 v209, v173, v108
	v_sub_f32_e32 v210, v174, v116
	v_fma_f32 v208, v196, v208, v100
	v_fma_f32 v209, v197, v209, v108
	v_fma_f32 v210, v198, v210, v116
	v_mul_f32_e32 v213, v209, v199
	v_fma_f32 v214, v132, v200, v221
	v_mul_f32_e32 v213, v213, v141
	v_mul_f32_e32 v215, v209, v214
	v_mul_f32_e32 v217, -1.0, v213
	v_mul_f32_e32 v216, v213, v132
	v_mul_f32_e32 v218, v211, v208
	v_fmac_f32_e32 v218, v142, v217
	ds_write2st64_b32 v222, v217, v218 offset0:0 offset1:1
	v_mul_f32_e32 v219, v216, v212
	v_mul_f32_e32 v220, v215, v212
	ds_write2st64_b32 v222, v211, v219 offset0:2 offset1:3
	ds_write_b32 v222, v220 offset:1024
	ds_write_b32 v223, v210 offset:0
	v_mul_f32_e32 v214, 0x3d800000, v143
	ds_write_b32 v223, v214 offset:8
	v_mul_f32_e32 v204, 0xbfb8aa3b, v125
	v_mul_f32_e32 v205, 0x3fb8aa3b, v125
	v_sub_f32_e32 v208, v100, v101
	v_exp_f32_e32 v206, v204
	v_exp_f32_e32 v207, v205
	v_sub_f32_e32 v209, v108, v109
	v_sub_f32_e32 v210, v116, v117
	v_fma_f32 v208, v196, v208, v101
	v_fma_f32 v209, v197, v209, v109
	v_fma_f32 v210, v198, v210, v117
	v_mul_f32_e32 v213, v209, v199
	v_fma_f32 v214, v133, v200, v221
	v_mul_f32_e32 v213, v213, v145
	v_mul_f32_e32 v215, v209, v214
	v_mul_f32_e64 v217, -v213, v211
	v_mul_f32_e32 v211, v211, v206
	v_mul_f32_e32 v212, v212, v207
	v_mul_f32_e32 v216, v213, v133
	v_mul_f32_e32 v218, v211, v208
	v_fmac_f32_e32 v218, v146, v217
	ds_write2st64_b32 v222, v217, v218 offset0:7 offset1:8
	v_mul_f32_e32 v219, v216, v212
	v_mul_f32_e32 v220, v215, v212
	ds_write2st64_b32 v222, v211, v219 offset0:9 offset1:10
	ds_write_b32 v222, v220 offset:2816
	ds_write_b32 v223, v210 offset:1792
	v_mul_f32_e32 v214, 0x3d800000, v147
	ds_write_b32 v223, v214 offset:1800
	v_mul_f32_e32 v204, 0xbfb8aa3b, v126
	v_mul_f32_e32 v205, 0x3fb8aa3b, v126
	v_sub_f32_e32 v208, v101, v102
	v_exp_f32_e32 v206, v204
	v_exp_f32_e32 v207, v205
	v_sub_f32_e32 v209, v109, v110
	v_sub_f32_e32 v210, v117, v118
	v_fma_f32 v208, v196, v208, v102
	v_fma_f32 v209, v197, v209, v110
	v_fma_f32 v210, v198, v210, v118
	v_mul_f32_e32 v213, v209, v199
	v_fma_f32 v214, v134, v200, v221
	v_mul_f32_e32 v213, v213, v149
	v_mul_f32_e32 v215, v209, v214
	v_mul_f32_e64 v217, -v213, v211
	v_mul_f32_e32 v211, v211, v206
	v_mul_f32_e32 v212, v212, v207
	v_mul_f32_e32 v216, v213, v134
	v_mul_f32_e32 v218, v211, v208
	v_fmac_f32_e32 v218, v150, v217
	ds_write2st64_b32 v222, v217, v218 offset0:14 offset1:15
	v_mul_f32_e32 v219, v216, v212
	v_mul_f32_e32 v220, v215, v212
	ds_write2st64_b32 v222, v211, v219 offset0:16 offset1:17
	ds_write_b32 v222, v220 offset:4608
	ds_write_b32 v223, v210 offset:3584
	v_mul_f32_e32 v214, 0x3d800000, v151
	ds_write_b32 v223, v214 offset:3592
	v_mul_f32_e32 v204, 0xbfb8aa3b, v127
	v_mul_f32_e32 v205, 0x3fb8aa3b, v127
	v_sub_f32_e32 v208, v102, v103
	v_exp_f32_e32 v206, v204
	v_exp_f32_e32 v207, v205
	v_sub_f32_e32 v209, v110, v111
	v_sub_f32_e32 v210, v118, v119
	v_fma_f32 v208, v196, v208, v103
	v_fma_f32 v209, v197, v209, v111
	v_fma_f32 v210, v198, v210, v119
	v_mul_f32_e32 v213, v209, v199
	v_fma_f32 v214, v135, v200, v221
	v_mul_f32_e32 v213, v213, v153
	v_mul_f32_e32 v215, v209, v214
	v_mul_f32_e64 v217, -v213, v211
	v_mul_f32_e32 v211, v211, v206
	v_mul_f32_e32 v212, v212, v207
	v_mul_f32_e32 v216, v213, v135
	v_mul_f32_e32 v218, v211, v208
	v_fmac_f32_e32 v218, v154, v217
	ds_write2st64_b32 v222, v217, v218 offset0:21 offset1:22
	v_mul_f32_e32 v219, v216, v212
	v_mul_f32_e32 v220, v215, v212
	ds_write2st64_b32 v222, v211, v219 offset0:23 offset1:24
	ds_write_b32 v222, v220 offset:6400
	ds_write_b32 v223, v210 offset:5376
	v_mul_f32_e32 v214, 0x3d800000, v155
	ds_write_b32 v223, v214 offset:5384
	v_mul_f32_e32 v204, 0xbfb8aa3b, v128
	v_mul_f32_e32 v205, 0x3fb8aa3b, v128
	v_sub_f32_e32 v208, v103, v104
	v_exp_f32_e32 v206, v204
	v_exp_f32_e32 v207, v205
	v_sub_f32_e32 v209, v111, v112
	v_sub_f32_e32 v210, v119, v120
	v_fma_f32 v208, v196, v208, v104
	v_fma_f32 v209, v197, v209, v112
	v_fma_f32 v210, v198, v210, v120
	v_mul_f32_e32 v213, v209, v199
	v_fma_f32 v214, v136, v200, v221
	v_mul_f32_e32 v213, v213, v157
	v_mul_f32_e32 v215, v209, v214
	v_mul_f32_e64 v217, -v213, v211
	v_mul_f32_e32 v211, v211, v206
	v_mul_f32_e32 v212, v212, v207
	v_mul_f32_e32 v216, v213, v136
	v_mul_f32_e32 v218, v211, v208
	v_fmac_f32_e32 v218, v158, v217
	ds_write2st64_b32 v222, v217, v218 offset0:28 offset1:29
	v_mul_f32_e32 v219, v216, v212
	v_mul_f32_e32 v220, v215, v212
	ds_write2st64_b32 v222, v211, v219 offset0:30 offset1:31
	ds_write_b32 v222, v220 offset:8192
	ds_write_b32 v223, v210 offset:7168
	v_mul_f32_e32 v214, 0x3d800000, v159
	ds_write_b32 v223, v214 offset:7176
	v_mul_f32_e32 v204, 0xbfb8aa3b, v129
	v_mul_f32_e32 v205, 0x3fb8aa3b, v129
	v_sub_f32_e32 v208, v104, v105
	v_exp_f32_e32 v206, v204
	v_exp_f32_e32 v207, v205
	v_sub_f32_e32 v209, v112, v113
	v_sub_f32_e32 v210, v120, v121
	v_fma_f32 v208, v196, v208, v105
	v_fma_f32 v209, v197, v209, v113
	v_fma_f32 v210, v198, v210, v121
	v_mul_f32_e32 v213, v209, v199
	v_fma_f32 v214, v137, v200, v221
	v_mul_f32_e32 v213, v213, v161
	v_mul_f32_e32 v215, v209, v214
	v_mul_f32_e64 v217, -v213, v211
	v_mul_f32_e32 v211, v211, v206
	v_mul_f32_e32 v212, v212, v207
	v_mul_f32_e32 v216, v213, v137
	v_mul_f32_e32 v218, v211, v208
	v_fmac_f32_e32 v218, v162, v217
	ds_write2st64_b32 v222, v217, v218 offset0:35 offset1:36
	v_mul_f32_e32 v219, v216, v212
	v_mul_f32_e32 v220, v215, v212
	ds_write2st64_b32 v222, v211, v219 offset0:37 offset1:38
	ds_write_b32 v222, v220 offset:9984
	ds_write_b32 v223, v210 offset:8960
	v_mul_f32_e32 v214, 0x3d800000, v163
	ds_write_b32 v223, v214 offset:8968
	v_mul_f32_e32 v204, 0xbfb8aa3b, v130
	v_mul_f32_e32 v205, 0x3fb8aa3b, v130
	v_sub_f32_e32 v208, v105, v106
	v_exp_f32_e32 v206, v204
	v_exp_f32_e32 v207, v205
	v_sub_f32_e32 v209, v113, v114
	v_sub_f32_e32 v210, v121, v122
	v_fma_f32 v208, v196, v208, v106
	v_fma_f32 v209, v197, v209, v114
	v_fma_f32 v210, v198, v210, v122
	v_mul_f32_e32 v213, v209, v199
	v_fma_f32 v214, v138, v200, v221
	v_mul_f32_e32 v213, v213, v165
	v_mul_f32_e32 v215, v209, v214
	v_mul_f32_e64 v217, -v213, v211
	v_mul_f32_e32 v211, v211, v206
	v_mul_f32_e32 v212, v212, v207
	v_mul_f32_e32 v216, v213, v138
	v_mul_f32_e32 v218, v211, v208
	v_fmac_f32_e32 v218, v166, v217
	ds_write2st64_b32 v222, v217, v218 offset0:42 offset1:43
	v_mul_f32_e32 v219, v216, v212
	v_mul_f32_e32 v220, v215, v212
	ds_write2st64_b32 v222, v211, v219 offset0:44 offset1:45
	ds_write_b32 v222, v220 offset:11776
	ds_write_b32 v223, v210 offset:10752
	v_mul_f32_e32 v214, 0x3d800000, v167
	ds_write_b32 v223, v214 offset:10760
	v_mul_f32_e32 v204, 0xbfb8aa3b, v131
	v_mul_f32_e32 v205, 0x3fb8aa3b, v131
	v_sub_f32_e32 v208, v106, v107
	v_exp_f32_e32 v206, v204
	v_exp_f32_e32 v207, v205
	v_sub_f32_e32 v209, v114, v115
	v_sub_f32_e32 v210, v122, v123
	v_fma_f32 v208, v196, v208, v107
	v_fma_f32 v209, v197, v209, v115
	v_fma_f32 v210, v198, v210, v123
	v_mul_f32_e32 v213, v209, v199
	v_fma_f32 v214, v139, v200, v221
	v_mul_f32_e32 v213, v213, v169
	v_mul_f32_e32 v215, v209, v214
	v_mul_f32_e64 v217, -v213, v211
	v_mul_f32_e32 v211, v211, v206
	v_mul_f32_e32 v212, v212, v207
	v_mul_f32_e32 v216, v213, v139
	v_mul_f32_e32 v218, v211, v208
	v_fmac_f32_e32 v218, v170, v217
	ds_write2st64_b32 v222, v217, v218 offset0:49 offset1:50
	v_mul_f32_e32 v219, v216, v212
	v_mul_f32_e32 v220, v215, v212
	ds_write2st64_b32 v222, v211, v219 offset0:51 offset1:52
	ds_write_b32 v222, v220 offset:13568
	ds_write_b32 v223, v210 offset:12544
	v_mul_f32_e32 v214, 0x3d800000, v171
	ds_write_b32 v223, v214 offset:12552
	s_cmp_gt_u32 s30, 33
	s_cbranch_scc1 .Lya_done
	s_cmp_eq_u32 s48, 0x100
	s_cbranch_scc0 .Lya_done
	v_mul_f32_e32 v247, 0x3b000000, v247
	v_add_f32_e32 v247, 0x3727c5ac, v247
	v_rsq_f32_e32 v247, v247
	v_lshlrev_b32_e32 v230, 16, v242
	v_and_b32_e32 v231, 0xffff0000, v242
	v_mul_f32_e32 v246, v247, v234
	v_mul_f32_e32 v230, v230, v246
	v_mul_f32_e32 v246, v247, v235
	v_mul_f32_e32 v231, v231, v246
	v_cvt_pk_bf16_f32 v242, v230, v231
	v_lshlrev_b32_e32 v230, 16, v243
	v_and_b32_e32 v231, 0xffff0000, v243
	v_mul_f32_e32 v246, v247, v236
	v_mul_f32_e32 v230, v230, v246
	v_mul_f32_e32 v246, v247, v237
	v_mul_f32_e32 v231, v231, v246
	v_cvt_pk_bf16_f32 v243, v230, v231
	v_lshlrev_b32_e32 v230, 16, v244
	v_and_b32_e32 v231, 0xffff0000, v244
	v_mul_f32_e32 v246, v247, v238
	v_mul_f32_e32 v230, v230, v246
	v_mul_f32_e32 v246, v247, v239
	v_mul_f32_e32 v231, v231, v246
	v_cvt_pk_bf16_f32 v244, v230, v231
	v_lshlrev_b32_e32 v230, 16, v245
	v_and_b32_e32 v231, 0xffff0000, v245
	v_mul_f32_e32 v246, v247, v240
	v_mul_f32_e32 v230, v230, v246
	v_mul_f32_e32 v246, v247, v241
	v_mul_f32_e32 v231, v231, v246
	v_cvt_pk_bf16_f32 v245, v230, v231
	v_mul_f32_e32 v248, 0x3b000000, v248
	v_add_f32_e32 v248, 0x3727c5ac, v248
	v_rsq_f32_e32 v248, v248
	v_lshlrev_b32_e32 v230, 16, v226
	v_and_b32_e32 v231, 0xffff0000, v226
	v_mul_f32_e32 v246, v248, v234
	v_mul_f32_e32 v230, v230, v246
	v_mul_f32_e32 v246, v248, v235
	v_mul_f32_e32 v231, v231, v246
	v_cvt_pk_bf16_f32 v226, v230, v231
	v_lshlrev_b32_e32 v230, 16, v227
	v_and_b32_e32 v231, 0xffff0000, v227
	v_mul_f32_e32 v246, v248, v236
	v_mul_f32_e32 v230, v230, v246
	v_mul_f32_e32 v246, v248, v237
	v_mul_f32_e32 v231, v231, v246
	v_cvt_pk_bf16_f32 v227, v230, v231
	v_lshlrev_b32_e32 v230, 16, v228
	v_and_b32_e32 v231, 0xffff0000, v228
	v_mul_f32_e32 v246, v248, v238
	v_mul_f32_e32 v230, v230, v246
	v_mul_f32_e32 v246, v248, v239
	v_mul_f32_e32 v231, v231, v246
	v_cvt_pk_bf16_f32 v228, v230, v231
	v_lshlrev_b32_e32 v230, 16, v229
	v_and_b32_e32 v231, 0xffff0000, v229
	v_mul_f32_e32 v246, v248, v240
	v_mul_f32_e32 v230, v230, v246
	v_mul_f32_e32 v246, v248, v241
	v_mul_f32_e32 v231, v231, v246
	v_cvt_pk_bf16_f32 v229, v230, v231
	s_mov_b32 s55, s30
	s_lshl_b32 s54, s55, 9
	s_add_u32 s54, s54, s2
	s_mul_i32 s52, s54, 0x5200
	s_add_u32 s52, s20, s52
	s_addc_u32 s53, s21, 0
	global_store_dwordx4 v233, v[242:245], s[52:53]
	s_add_u32 s52, s52, 0x520000
	s_addc_u32 s53, s53, 0
	global_store_dwordx4 v233, v[226:229], s[52:53]
	s_cmp_eq_u32 s30, 33
	s_cbranch_scc1 .Lya_done
	s_add_u32 s55, s30, 1
	s_lshl_b32 s54, s55, 9
	s_add_u32 s54, s54, s2
	s_mul_i32 s52, s54, 0x5200
	s_add_u32 s52, s20, s52
	s_addc_u32 s53, s21, 0
	global_load_dwordx4 v[242:245], v233, s[52:53]
	s_add_u32 s52, s52, 0x520000
	s_addc_u32 s53, s53, 0
	global_load_dwordx4 v[226:229], v233, s[52:53]
	s_lshl_b32 s52, s54, 4
	s_lshl_b32 s53, s33, 2
	s_add_u32 s52, s52, s53
	s_add_u32 s52, s46, s52
	s_addc_u32 s53, s47, 0
	global_load_dword v247, v77, s[52:53]
	s_add_u32 s52, s52, 0x1000
	s_addc_u32 s53, s53, 0
	global_load_dword v248, v77, s[52:53]

.LBB0_1368:
	s_andn2_saveexec_b64 s[56:57], s[56:57]
	s_cbranch_execz .LBB0_1347
	s_cmp_lg_u32 s30, 0
	s_cbranch_scc1 .Lrwp_go
	v_and_b32_e32 v210, 15, v178
	v_lshlrev_b32_e32 v159, 4, v210
	v_lshlrev_b32_e32 v208, 3, v201
	v_add_u32_e32 v208, 0x500, v208
	v_mov_b32_e32 v100, 0
	v_mov_b32_e32 v101, 0
	v_mov_b32_e32 v102, 0
	v_mov_b32_e32 v103, 0
	v_mov_b32_e32 v104, 0
	v_mov_b32_e32 v105, 0
	v_mov_b32_e32 v106, 0
	v_mov_b32_e32 v107, 0
	v_and_b32_e32 v194, 3, v178
.Lrwp_go:
	v_cmp_eq_u32_e64 s[52:53], 1, v194
	v_cmp_eq_u32_e64 s[54:55], 2, v194
	v_cmp_eq_u32_e32 vcc, 3, v194
	s_setprio 3
	s_and_b32 s0, s30, 1
	s_mul_i32 s0, s0, 0xe000
	s_movk_i32 s33, 0x5200
	v_add_u32_e32 v156, s0, v159
	v_add_u32_e32 v157, s0, v208
	s_mov_b32 s60, 0x52000
	s_mov_b32 s61, 0
	ds_read_b128 v[108:111], v156 offset:0
	ds_read_b128 v[112:115], v156 offset:256
	ds_read_b128 v[120:123], v156 offset:1024
	ds_read_b128 v[124:127], v157 offset:0
	ds_read_b128 v[116:119], v156 offset:768
	v_mad_u64_u32 v[160:161], s[58:59], v210, s33, v[88:89]
	s_waitcnt lgkmcnt(0)
	ds_read_b128 v[128:131], v156 offset:1792
	ds_read_b128 v[132:135], v156 offset:2048
	ds_read_b128 v[140:143], v156 offset:2816
	ds_read_b128 v[144:147], v157 offset:1792
	ds_read_b128 v[136:139], v156 offset:2560
	v_pk_mul_f32 v[148:149], v[100:101], v[108:109] op_sel_hi:[1,0]
	v_pk_mul_f32 v[150:151], v[100:101], v[112:113] op_sel_hi:[1,0]
	v_pk_fma_f32 v[148:149], v[102:103], v[108:109], v[148:149] op_sel:[0,1,0]
	v_pk_fma_f32 v[150:151], v[102:103], v[112:113], v[150:151] op_sel:[0,1,0]
	v_pk_fma_f32 v[148:149], v[104:105], v[110:111], v[148:149] op_sel_hi:[1,0,1]
	v_pk_fma_f32 v[150:151], v[104:105], v[114:115], v[150:151] op_sel_hi:[1,0,1]
	v_pk_fma_f32 v[148:149], v[106:107], v[110:111], v[148:149] op_sel:[0,1,0]
	v_pk_fma_f32 v[150:151], v[106:107], v[114:115], v[150:151] op_sel:[0,1,0]
	v_pk_fma_f32 v[100:101], v[124:125], v[120:121], v[100:101] op_sel_hi:[1,0,1]
	v_add_f32_dpp v148, v148, v148 quad_perm:[1,0,3,2] row_mask:0xf bank_mask:0xf bound_ctrl:1
	v_add_f32_dpp v149, v149, v149 quad_perm:[1,0,3,2] row_mask:0xf bank_mask:0xf bound_ctrl:1
	v_pk_fma_f32 v[102:103], v[124:125], v[120:121], v[102:103] op_sel:[0,1,0]
	v_pk_fma_f32 v[212:213], v[124:125], v[126:127], v[150:151] op_sel_hi:[1,0,1]
	v_add_f32_dpp v148, v148, v148 quad_perm:[2,3,0,1] row_mask:0xf bank_mask:0xf bound_ctrl:1
	v_add_f32_dpp v149, v149, v149 quad_perm:[2,3,0,1] row_mask:0xf bank_mask:0xf bound_ctrl:1
	v_pk_fma_f32 v[104:105], v[124:125], v[122:123], v[104:105] op_sel_hi:[1,0,1]
	v_pk_fma_f32 v[106:107], v[124:125], v[122:123], v[106:107] op_sel:[0,1,0]
	v_add_f32_dpp v148, v148, v148 row_half_mirror row_mask:0xf bank_mask:0xf bound_ctrl:1
	v_add_f32_dpp v149, v149, v149 row_half_mirror row_mask:0xf bank_mask:0xf bound_ctrl:1
	s_nop 1
	v_add_f32_dpp v148, v148, v148 row_mirror row_mask:0xf bank_mask:0xf bound_ctrl:1
	v_add_f32_dpp v149, v149, v149 row_mirror row_mask:0xf bank_mask:0xf bound_ctrl:1
	v_pk_fma_f32 v[100:101], v[148:149], v[116:117], v[100:101] op_sel_hi:[1,0,1]
	v_pk_fma_f32 v[102:103], v[148:149], v[116:117], v[102:103] op_sel:[0,1,0]
	v_pk_fma_f32 v[104:105], v[148:149], v[118:119], v[104:105] op_sel_hi:[1,0,1]
	v_pk_fma_f32 v[106:107], v[148:149], v[118:119], v[106:107] op_sel:[0,1,0]
	s_waitcnt lgkmcnt(0)
	ds_read_b128 v[108:111], v156 offset:3584
	ds_read_b128 v[112:115], v156 offset:3840
	ds_read_b128 v[120:123], v156 offset:4608
	ds_read_b128 v[124:127], v157 offset:3584
	ds_read_b128 v[116:119], v156 offset:4352
	v_pk_mul_f32 v[148:149], v[100:101], v[128:129] op_sel_hi:[1,0]
	v_pk_mul_f32 v[150:151], v[100:101], v[132:133] op_sel_hi:[1,0]
	v_pk_fma_f32 v[148:149], v[102:103], v[128:129], v[148:149] op_sel:[0,1,0]
	v_pk_fma_f32 v[150:151], v[102:103], v[132:133], v[150:151] op_sel:[0,1,0]
	v_pk_fma_f32 v[148:149], v[104:105], v[130:131], v[148:149] op_sel_hi:[1,0,1]
	v_pk_fma_f32 v[150:151], v[104:105], v[134:135], v[150:151] op_sel_hi:[1,0,1]
	v_pk_fma_f32 v[148:149], v[106:107], v[130:131], v[148:149] op_sel:[0,1,0]
	v_pk_fma_f32 v[150:151], v[106:107], v[134:135], v[150:151] op_sel:[0,1,0]
	v_pk_fma_f32 v[100:101], v[144:145], v[140:141], v[100:101] op_sel_hi:[1,0,1]
	v_add_f32_dpp v148, v148, v148 quad_perm:[1,0,3,2] row_mask:0xf bank_mask:0xf bound_ctrl:1
	v_add_f32_dpp v149, v149, v149 quad_perm:[1,0,3,2] row_mask:0xf bank_mask:0xf bound_ctrl:1
	v_pk_fma_f32 v[102:103], v[144:145], v[140:141], v[102:103] op_sel:[0,1,0]
	v_pk_fma_f32 v[214:215], v[144:145], v[146:147], v[150:151] op_sel_hi:[1,0,1]
	v_add_f32_dpp v148, v148, v148 quad_perm:[2,3,0,1] row_mask:0xf bank_mask:0xf bound_ctrl:1
	v_add_f32_dpp v149, v149, v149 quad_perm:[2,3,0,1] row_mask:0xf bank_mask:0xf bound_ctrl:1
	v_pk_fma_f32 v[104:105], v[144:145], v[142:143], v[104:105] op_sel_hi:[1,0,1]
	v_pk_fma_f32 v[106:107], v[144:145], v[142:143], v[106:107] op_sel:[0,1,0]
	v_add_f32_dpp v148, v148, v148 row_half_mirror row_mask:0xf bank_mask:0xf bound_ctrl:1
	v_add_f32_dpp v149, v149, v149 row_half_mirror row_mask:0xf bank_mask:0xf bound_ctrl:1
	s_nop 1
	v_add_f32_dpp v148, v148, v148 row_mirror row_mask:0xf bank_mask:0xf bound_ctrl:1
	v_add_f32_dpp v149, v149, v149 row_mirror row_mask:0xf bank_mask:0xf bound_ctrl:1
	v_pk_fma_f32 v[100:101], v[148:149], v[136:137], v[100:101] op_sel_hi:[1,0,1]
	v_pk_fma_f32 v[102:103], v[148:149], v[136:137], v[102:103] op_sel:[0,1,0]
	v_pk_fma_f32 v[104:105], v[148:149], v[138:139], v[104:105] op_sel_hi:[1,0,1]
	v_pk_fma_f32 v[106:107], v[148:149], v[138:139], v[106:107] op_sel:[0,1,0]
	s_waitcnt lgkmcnt(0)
	ds_read_b128 v[128:131], v156 offset:5376
	ds_read_b128 v[132:135], v156 offset:5632
	ds_read_b128 v[140:143], v156 offset:6400
	ds_read_b128 v[144:147], v157 offset:5376
	ds_read_b128 v[136:139], v156 offset:6144
	v_pk_mul_f32 v[148:149], v[100:101], v[108:109] op_sel_hi:[1,0]
	v_pk_mul_f32 v[150:151], v[100:101], v[112:113] op_sel_hi:[1,0]
	v_pk_fma_f32 v[148:149], v[102:103], v[108:109], v[148:149] op_sel:[0,1,0]
	v_pk_fma_f32 v[150:151], v[102:103], v[112:113], v[150:151] op_sel:[0,1,0]
	v_pk_fma_f32 v[148:149], v[104:105], v[110:111], v[148:149] op_sel_hi:[1,0,1]
	v_pk_fma_f32 v[150:151], v[104:105], v[114:115], v[150:151] op_sel_hi:[1,0,1]
	v_pk_fma_f32 v[148:149], v[106:107], v[110:111], v[148:149] op_sel:[0,1,0]
	v_pk_fma_f32 v[150:151], v[106:107], v[114:115], v[150:151] op_sel:[0,1,0]
	v_pk_fma_f32 v[100:101], v[124:125], v[120:121], v[100:101] op_sel_hi:[1,0,1]
	v_add_f32_dpp v148, v148, v148 quad_perm:[1,0,3,2] row_mask:0xf bank_mask:0xf bound_ctrl:1
	v_add_f32_dpp v149, v149, v149 quad_perm:[1,0,3,2] row_mask:0xf bank_mask:0xf bound_ctrl:1
	v_pk_fma_f32 v[102:103], v[124:125], v[120:121], v[102:103] op_sel:[0,1,0]
	v_pk_fma_f32 v[216:217], v[124:125], v[126:127], v[150:151] op_sel_hi:[1,0,1]
	v_add_f32_dpp v148, v148, v148 quad_perm:[2,3,0,1] row_mask:0xf bank_mask:0xf bound_ctrl:1
	v_add_f32_dpp v149, v149, v149 quad_perm:[2,3,0,1] row_mask:0xf bank_mask:0xf bound_ctrl:1
	v_pk_fma_f32 v[104:105], v[124:125], v[122:123], v[104:105] op_sel_hi:[1,0,1]
	v_pk_fma_f32 v[106:107], v[124:125], v[122:123], v[106:107] op_sel:[0,1,0]
	v_add_f32_dpp v148, v148, v148 row_half_mirror row_mask:0xf bank_mask:0xf bound_ctrl:1
	v_add_f32_dpp v149, v149, v149 row_half_mirror row_mask:0xf bank_mask:0xf bound_ctrl:1
	s_nop 1
	v_add_f32_dpp v148, v148, v148 row_mirror row_mask:0xf bank_mask:0xf bound_ctrl:1
	v_add_f32_dpp v149, v149, v149 row_mirror row_mask:0xf bank_mask:0xf bound_ctrl:1
	v_pk_fma_f32 v[100:101], v[148:149], v[116:117], v[100:101] op_sel_hi:[1,0,1]
	v_pk_fma_f32 v[102:103], v[148:149], v[116:117], v[102:103] op_sel:[0,1,0]
	v_pk_fma_f32 v[104:105], v[148:149], v[118:119], v[104:105] op_sel_hi:[1,0,1]
	v_pk_fma_f32 v[106:107], v[148:149], v[118:119], v[106:107] op_sel:[0,1,0]
	s_waitcnt lgkmcnt(0)
	ds_read_b128 v[108:111], v156 offset:7168
	ds_read_b128 v[112:115], v156 offset:7424
	ds_read_b128 v[120:123], v156 offset:8192
	ds_read_b128 v[124:127], v157 offset:7168
	ds_read_b128 v[116:119], v156 offset:7936
	v_pk_mul_f32 v[148:149], v[100:101], v[128:129] op_sel_hi:[1,0]
	v_pk_mul_f32 v[150:151], v[100:101], v[132:133] op_sel_hi:[1,0]
	v_pk_fma_f32 v[148:149], v[102:103], v[128:129], v[148:149] op_sel:[0,1,0]
	v_pk_fma_f32 v[150:151], v[102:103], v[132:133], v[150:151] op_sel:[0,1,0]
	v_pk_fma_f32 v[148:149], v[104:105], v[130:131], v[148:149] op_sel_hi:[1,0,1]
	v_pk_fma_f32 v[150:151], v[104:105], v[134:135], v[150:151] op_sel_hi:[1,0,1]
	v_pk_fma_f32 v[148:149], v[106:107], v[130:131], v[148:149] op_sel:[0,1,0]
	v_pk_fma_f32 v[150:151], v[106:107], v[134:135], v[150:151] op_sel:[0,1,0]
	v_pk_fma_f32 v[100:101], v[144:145], v[140:141], v[100:101] op_sel_hi:[1,0,1]
	v_add_f32_dpp v148, v148, v148 quad_perm:[1,0,3,2] row_mask:0xf bank_mask:0xf bound_ctrl:1
	v_add_f32_dpp v149, v149, v149 quad_perm:[1,0,3,2] row_mask:0xf bank_mask:0xf bound_ctrl:1
	v_pk_fma_f32 v[102:103], v[144:145], v[140:141], v[102:103] op_sel:[0,1,0]
	v_pk_fma_f32 v[218:219], v[144:145], v[146:147], v[150:151] op_sel_hi:[1,0,1]
	v_add_f32_dpp v148, v148, v148 quad_perm:[2,3,0,1] row_mask:0xf bank_mask:0xf bound_ctrl:1
	v_add_f32_dpp v149, v149, v149 quad_perm:[2,3,0,1] row_mask:0xf bank_mask:0xf bound_ctrl:1
	v_pk_fma_f32 v[104:105], v[144:145], v[142:143], v[104:105] op_sel_hi:[1,0,1]
	v_pk_fma_f32 v[106:107], v[144:145], v[142:143], v[106:107] op_sel:[0,1,0]
	v_add_f32_dpp v148, v148, v148 row_half_mirror row_mask:0xf bank_mask:0xf bound_ctrl:1
	v_add_f32_dpp v149, v149, v149 row_half_mirror row_mask:0xf bank_mask:0xf bound_ctrl:1
	s_nop 1
	v_add_f32_dpp v148, v148, v148 row_mirror row_mask:0xf bank_mask:0xf bound_ctrl:1
	v_add_f32_dpp v149, v149, v149 row_mirror row_mask:0xf bank_mask:0xf bound_ctrl:1
	v_pk_fma_f32 v[100:101], v[148:149], v[136:137], v[100:101] op_sel_hi:[1,0,1]
	v_pk_fma_f32 v[102:103], v[148:149], v[136:137], v[102:103] op_sel:[0,1,0]
	v_pk_fma_f32 v[104:105], v[148:149], v[138:139], v[104:105] op_sel_hi:[1,0,1]
	v_pk_fma_f32 v[106:107], v[148:149], v[138:139], v[106:107] op_sel:[0,1,0]
	s_waitcnt lgkmcnt(0)
	ds_read_b128 v[128:131], v156 offset:8960
	ds_read_b128 v[132:135], v156 offset:9216
	ds_read_b128 v[140:143], v156 offset:9984
	ds_read_b128 v[144:147], v157 offset:8960
	ds_read_b128 v[136:139], v156 offset:9728
	v_pk_mul_f32 v[148:149], v[100:101], v[108:109] op_sel_hi:[1,0]
	v_pk_mul_f32 v[150:151], v[100:101], v[112:113] op_sel_hi:[1,0]
	v_pk_fma_f32 v[148:149], v[102:103], v[108:109], v[148:149] op_sel:[0,1,0]
	v_pk_fma_f32 v[150:151], v[102:103], v[112:113], v[150:151] op_sel:[0,1,0]
	v_pk_fma_f32 v[148:149], v[104:105], v[110:111], v[148:149] op_sel_hi:[1,0,1]
	v_pk_fma_f32 v[150:151], v[104:105], v[114:115], v[150:151] op_sel_hi:[1,0,1]
	v_pk_fma_f32 v[148:149], v[106:107], v[110:111], v[148:149] op_sel:[0,1,0]
	v_pk_fma_f32 v[150:151], v[106:107], v[114:115], v[150:151] op_sel:[0,1,0]
	v_pk_fma_f32 v[100:101], v[124:125], v[120:121], v[100:101] op_sel_hi:[1,0,1]
	v_add_f32_dpp v148, v148, v148 quad_perm:[1,0,3,2] row_mask:0xf bank_mask:0xf bound_ctrl:1
	v_add_f32_dpp v149, v149, v149 quad_perm:[1,0,3,2] row_mask:0xf bank_mask:0xf bound_ctrl:1
	v_pk_fma_f32 v[102:103], v[124:125], v[120:121], v[102:103] op_sel:[0,1,0]
	v_pk_fma_f32 v[220:221], v[124:125], v[126:127], v[150:151] op_sel_hi:[1,0,1]
	v_add_f32_dpp v148, v148, v148 quad_perm:[2,3,0,1] row_mask:0xf bank_mask:0xf bound_ctrl:1
	v_add_f32_dpp v149, v149, v149 quad_perm:[2,3,0,1] row_mask:0xf bank_mask:0xf bound_ctrl:1
	v_pk_fma_f32 v[104:105], v[124:125], v[122:123], v[104:105] op_sel_hi:[1,0,1]
	v_pk_fma_f32 v[106:107], v[124:125], v[122:123], v[106:107] op_sel:[0,1,0]
	v_add_f32_dpp v148, v148, v148 row_half_mirror row_mask:0xf bank_mask:0xf bound_ctrl:1
	v_add_f32_dpp v149, v149, v149 row_half_mirror row_mask:0xf bank_mask:0xf bound_ctrl:1
	s_nop 1
	v_add_f32_dpp v148, v148, v148 row_mirror row_mask:0xf bank_mask:0xf bound_ctrl:1
	v_add_f32_dpp v149, v149, v149 row_mirror row_mask:0xf bank_mask:0xf bound_ctrl:1
	v_pk_fma_f32 v[100:101], v[148:149], v[116:117], v[100:101] op_sel_hi:[1,0,1]
	v_pk_fma_f32 v[102:103], v[148:149], v[116:117], v[102:103] op_sel:[0,1,0]
	v_pk_fma_f32 v[104:105], v[148:149], v[118:119], v[104:105] op_sel_hi:[1,0,1]
	v_pk_fma_f32 v[106:107], v[148:149], v[118:119], v[106:107] op_sel:[0,1,0]
	s_waitcnt lgkmcnt(0)
	ds_read_b128 v[108:111], v156 offset:10752
	ds_read_b128 v[112:115], v156 offset:11008
	ds_read_b128 v[120:123], v156 offset:11776
	ds_read_b128 v[124:127], v157 offset:10752
	ds_read_b128 v[116:119], v156 offset:11520
	v_pk_mul_f32 v[148:149], v[100:101], v[128:129] op_sel_hi:[1,0]
	v_pk_mul_f32 v[150:151], v[100:101], v[132:133] op_sel_hi:[1,0]
	v_pk_fma_f32 v[148:149], v[102:103], v[128:129], v[148:149] op_sel:[0,1,0]
	v_pk_fma_f32 v[150:151], v[102:103], v[132:133], v[150:151] op_sel:[0,1,0]
	v_pk_fma_f32 v[148:149], v[104:105], v[130:131], v[148:149] op_sel_hi:[1,0,1]
	v_pk_fma_f32 v[150:151], v[104:105], v[134:135], v[150:151] op_sel_hi:[1,0,1]
	v_pk_fma_f32 v[148:149], v[106:107], v[130:131], v[148:149] op_sel:[0,1,0]
	v_pk_fma_f32 v[150:151], v[106:107], v[134:135], v[150:151] op_sel:[0,1,0]
	v_pk_fma_f32 v[100:101], v[144:145], v[140:141], v[100:101] op_sel_hi:[1,0,1]
	v_add_f32_dpp v148, v148, v148 quad_perm:[1,0,3,2] row_mask:0xf bank_mask:0xf bound_ctrl:1
	v_add_f32_dpp v149, v149, v149 quad_perm:[1,0,3,2] row_mask:0xf bank_mask:0xf bound_ctrl:1
	v_pk_fma_f32 v[102:103], v[144:145], v[140:141], v[102:103] op_sel:[0,1,0]
	v_pk_fma_f32 v[222:223], v[144:145], v[146:147], v[150:151] op_sel_hi:[1,0,1]
	v_add_f32_dpp v148, v148, v148 quad_perm:[2,3,0,1] row_mask:0xf bank_mask:0xf bound_ctrl:1
	v_add_f32_dpp v149, v149, v149 quad_perm:[2,3,0,1] row_mask:0xf bank_mask:0xf bound_ctrl:1
	v_pk_fma_f32 v[104:105], v[144:145], v[142:143], v[104:105] op_sel_hi:[1,0,1]
	v_pk_fma_f32 v[106:107], v[144:145], v[142:143], v[106:107] op_sel:[0,1,0]
	v_add_f32_dpp v148, v148, v148 row_half_mirror row_mask:0xf bank_mask:0xf bound_ctrl:1
	v_add_f32_dpp v149, v149, v149 row_half_mirror row_mask:0xf bank_mask:0xf bound_ctrl:1
	s_nop 1
	v_add_f32_dpp v148, v148, v148 row_mirror row_mask:0xf bank_mask:0xf bound_ctrl:1
	v_add_f32_dpp v149, v149, v149 row_mirror row_mask:0xf bank_mask:0xf bound_ctrl:1
	v_pk_fma_f32 v[100:101], v[148:149], v[136:137], v[100:101] op_sel_hi:[1,0,1]
	v_pk_fma_f32 v[102:103], v[148:149], v[136:137], v[102:103] op_sel:[0,1,0]
	v_pk_fma_f32 v[104:105], v[148:149], v[138:139], v[104:105] op_sel_hi:[1,0,1]
	v_pk_fma_f32 v[106:107], v[148:149], v[138:139], v[106:107] op_sel:[0,1,0]
	s_waitcnt lgkmcnt(0)
	ds_read_b128 v[128:131], v156 offset:12544
	ds_read_b128 v[132:135], v156 offset:12800
	ds_read_b128 v[140:143], v156 offset:13568
	ds_read_b128 v[144:147], v157 offset:12544
	ds_read_b128 v[136:139], v156 offset:13312
	v_pk_mul_f32 v[148:149], v[100:101], v[108:109] op_sel_hi:[1,0]
	v_pk_mul_f32 v[150:151], v[100:101], v[112:113] op_sel_hi:[1,0]
	v_pk_fma_f32 v[148:149], v[102:103], v[108:109], v[148:149] op_sel:[0,1,0]
	v_pk_fma_f32 v[150:151], v[102:103], v[112:113], v[150:151] op_sel:[0,1,0]
	v_pk_fma_f32 v[148:149], v[104:105], v[110:111], v[148:149] op_sel_hi:[1,0,1]
	v_pk_fma_f32 v[150:151], v[104:105], v[114:115], v[150:151] op_sel_hi:[1,0,1]
	v_pk_fma_f32 v[148:149], v[106:107], v[110:111], v[148:149] op_sel:[0,1,0]
	v_pk_fma_f32 v[150:151], v[106:107], v[114:115], v[150:151] op_sel:[0,1,0]
	v_pk_fma_f32 v[100:101], v[124:125], v[120:121], v[100:101] op_sel_hi:[1,0,1]
	v_add_f32_dpp v148, v148, v148 quad_perm:[1,0,3,2] row_mask:0xf bank_mask:0xf bound_ctrl:1
	v_add_f32_dpp v149, v149, v149 quad_perm:[1,0,3,2] row_mask:0xf bank_mask:0xf bound_ctrl:1
	v_pk_fma_f32 v[102:103], v[124:125], v[120:121], v[102:103] op_sel:[0,1,0]
	v_pk_fma_f32 v[224:225], v[124:125], v[126:127], v[150:151] op_sel_hi:[1,0,1]
	v_add_f32_dpp v148, v148, v148 quad_perm:[2,3,0,1] row_mask:0xf bank_mask:0xf bound_ctrl:1
	v_add_f32_dpp v149, v149, v149 quad_perm:[2,3,0,1] row_mask:0xf bank_mask:0xf bound_ctrl:1
	v_pk_fma_f32 v[104:105], v[124:125], v[122:123], v[104:105] op_sel_hi:[1,0,1]
	v_pk_fma_f32 v[106:107], v[124:125], v[122:123], v[106:107] op_sel:[0,1,0]
	v_add_f32_dpp v148, v148, v148 row_half_mirror row_mask:0xf bank_mask:0xf bound_ctrl:1
	v_add_f32_dpp v149, v149, v149 row_half_mirror row_mask:0xf bank_mask:0xf bound_ctrl:1
	s_nop 1
	v_add_f32_dpp v148, v148, v148 row_mirror row_mask:0xf bank_mask:0xf bound_ctrl:1
	v_add_f32_dpp v149, v149, v149 row_mirror row_mask:0xf bank_mask:0xf bound_ctrl:1
	v_pk_fma_f32 v[100:101], v[148:149], v[116:117], v[100:101] op_sel_hi:[1,0,1]
	v_pk_fma_f32 v[102:103], v[148:149], v[116:117], v[102:103] op_sel:[0,1,0]
	v_pk_fma_f32 v[104:105], v[148:149], v[118:119], v[104:105] op_sel_hi:[1,0,1]
	v_pk_fma_f32 v[106:107], v[148:149], v[118:119], v[106:107] op_sel:[0,1,0]
	s_waitcnt lgkmcnt(0)
	ds_read_b128 v[108:111], v156 offset:14336
	ds_read_b128 v[112:115], v156 offset:14592
	ds_read_b128 v[120:123], v156 offset:15360
	ds_read_b128 v[124:127], v157 offset:14336
	ds_read_b128 v[116:119], v156 offset:15104
	ds_read_b128 v[204:207], v156 offset:13056
	v_pk_mul_f32 v[148:149], v[100:101], v[128:129] op_sel_hi:[1,0]
	v_pk_mul_f32 v[150:151], v[100:101], v[132:133] op_sel_hi:[1,0]
	v_pk_fma_f32 v[148:149], v[102:103], v[128:129], v[148:149] op_sel:[0,1,0]
	v_pk_fma_f32 v[150:151], v[102:103], v[132:133], v[150:151] op_sel:[0,1,0]
	v_pk_fma_f32 v[148:149], v[104:105], v[130:131], v[148:149] op_sel_hi:[1,0,1]
	v_pk_fma_f32 v[150:151], v[104:105], v[134:135], v[150:151] op_sel_hi:[1,0,1]
	v_pk_fma_f32 v[148:149], v[106:107], v[130:131], v[148:149] op_sel:[0,1,0]
	v_pk_fma_f32 v[150:151], v[106:107], v[134:135], v[150:151] op_sel:[0,1,0]
	v_pk_fma_f32 v[100:101], v[144:145], v[140:141], v[100:101] op_sel_hi:[1,0,1]
	v_add_f32_dpp v148, v148, v148 quad_perm:[1,0,3,2] row_mask:0xf bank_mask:0xf bound_ctrl:1
	v_add_f32_dpp v149, v149, v149 quad_perm:[1,0,3,2] row_mask:0xf bank_mask:0xf bound_ctrl:1
	v_pk_fma_f32 v[102:103], v[144:145], v[140:141], v[102:103] op_sel:[0,1,0]
	v_pk_fma_f32 v[226:227], v[144:145], v[146:147], v[150:151] op_sel_hi:[1,0,1]
	v_add_f32_dpp v148, v148, v148 quad_perm:[2,3,0,1] row_mask:0xf bank_mask:0xf bound_ctrl:1
	v_add_f32_dpp v149, v149, v149 quad_perm:[2,3,0,1] row_mask:0xf bank_mask:0xf bound_ctrl:1
	v_pk_fma_f32 v[104:105], v[144:145], v[142:143], v[104:105] op_sel_hi:[1,0,1]
	v_pk_fma_f32 v[106:107], v[144:145], v[142:143], v[106:107] op_sel:[0,1,0]
	v_add_f32_dpp v148, v148, v148 row_half_mirror row_mask:0xf bank_mask:0xf bound_ctrl:1
	v_add_f32_dpp v149, v149, v149 row_half_mirror row_mask:0xf bank_mask:0xf bound_ctrl:1
	s_nop 1
	v_add_f32_dpp v148, v148, v148 row_mirror row_mask:0xf bank_mask:0xf bound_ctrl:1
	v_add_f32_dpp v149, v149, v149 row_mirror row_mask:0xf bank_mask:0xf bound_ctrl:1
	v_pk_fma_f32 v[100:101], v[148:149], v[136:137], v[100:101] op_sel_hi:[1,0,1]
	v_pk_fma_f32 v[102:103], v[148:149], v[136:137], v[102:103] op_sel:[0,1,0]
	v_pk_fma_f32 v[104:105], v[148:149], v[138:139], v[104:105] op_sel_hi:[1,0,1]
	v_pk_fma_f32 v[106:107], v[148:149], v[138:139], v[106:107] op_sel:[0,1,0]
	s_waitcnt lgkmcnt(0)
	v_pk_mul_f32 v[100:101], v[100:101], v[204:205] op_sel_hi:[1,0]
	v_pk_mul_f32 v[102:103], v[102:103], v[204:205] op_sel:[0,1]
	v_pk_mul_f32 v[104:105], v[104:105], v[206:207] op_sel_hi:[1,0]
	v_pk_mul_f32 v[106:107], v[106:107], v[206:207] op_sel:[0,1]
	ds_read_b128 v[128:131], v156 offset:16128
	ds_read_b128 v[132:135], v156 offset:16384
	ds_read_b128 v[140:143], v156 offset:17152
	ds_read_b128 v[144:147], v157 offset:16128
	ds_read_b128 v[136:139], v156 offset:16896
	v_pk_mul_f32 v[148:149], v[100:101], v[108:109] op_sel_hi:[1,0]
	v_pk_mul_f32 v[150:151], v[100:101], v[112:113] op_sel_hi:[1,0]
	v_pk_fma_f32 v[148:149], v[102:103], v[108:109], v[148:149] op_sel:[0,1,0]
	v_pk_fma_f32 v[150:151], v[102:103], v[112:113], v[150:151] op_sel:[0,1,0]
	v_pk_fma_f32 v[148:149], v[104:105], v[110:111], v[148:149] op_sel_hi:[1,0,1]
	v_pk_fma_f32 v[150:151], v[104:105], v[114:115], v[150:151] op_sel_hi:[1,0,1]
	v_pk_fma_f32 v[148:149], v[106:107], v[110:111], v[148:149] op_sel:[0,1,0]
	v_pk_fma_f32 v[150:151], v[106:107], v[114:115], v[150:151] op_sel:[0,1,0]
	v_pk_fma_f32 v[100:101], v[124:125], v[120:121], v[100:101] op_sel_hi:[1,0,1]
	v_add_f32_dpp v148, v148, v148 quad_perm:[1,0,3,2] row_mask:0xf bank_mask:0xf bound_ctrl:1
	v_add_f32_dpp v149, v149, v149 quad_perm:[1,0,3,2] row_mask:0xf bank_mask:0xf bound_ctrl:1
	v_pk_fma_f32 v[102:103], v[124:125], v[120:121], v[102:103] op_sel:[0,1,0]
	v_pk_fma_f32 v[228:229], v[124:125], v[126:127], v[150:151] op_sel_hi:[1,0,1]
	v_add_f32_dpp v148, v148, v148 quad_perm:[2,3,0,1] row_mask:0xf bank_mask:0xf bound_ctrl:1
	v_add_f32_dpp v149, v149, v149 quad_perm:[2,3,0,1] row_mask:0xf bank_mask:0xf bound_ctrl:1
	v_pk_fma_f32 v[104:105], v[124:125], v[122:123], v[104:105] op_sel_hi:[1,0,1]
	v_pk_fma_f32 v[106:107], v[124:125], v[122:123], v[106:107] op_sel:[0,1,0]
	v_add_f32_dpp v148, v148, v148 row_half_mirror row_mask:0xf bank_mask:0xf bound_ctrl:1
	v_add_f32_dpp v149, v149, v149 row_half_mirror row_mask:0xf bank_mask:0xf bound_ctrl:1
	s_nop 1
	v_add_f32_dpp v148, v148, v148 row_mirror row_mask:0xf bank_mask:0xf bound_ctrl:1
	v_add_f32_dpp v149, v149, v149 row_mirror row_mask:0xf bank_mask:0xf bound_ctrl:1
	v_pk_fma_f32 v[100:101], v[148:149], v[116:117], v[100:101] op_sel_hi:[1,0,1]
	v_pk_fma_f32 v[102:103], v[148:149], v[116:117], v[102:103] op_sel:[0,1,0]
	v_pk_fma_f32 v[104:105], v[148:149], v[118:119], v[104:105] op_sel_hi:[1,0,1]
	v_pk_fma_f32 v[106:107], v[148:149], v[118:119], v[106:107] op_sel:[0,1,0]
	s_waitcnt lgkmcnt(0)
	ds_read_b128 v[108:111], v156 offset:17920
	ds_read_b128 v[112:115], v156 offset:18176
	ds_read_b128 v[120:123], v156 offset:18944
	ds_read_b128 v[124:127], v157 offset:17920
	ds_read_b128 v[116:119], v156 offset:18688
	v_pk_mul_f32 v[148:149], v[100:101], v[128:129] op_sel_hi:[1,0]
	v_pk_mul_f32 v[150:151], v[100:101], v[132:133] op_sel_hi:[1,0]
	v_pk_fma_f32 v[148:149], v[102:103], v[128:129], v[148:149] op_sel:[0,1,0]
	v_pk_fma_f32 v[150:151], v[102:103], v[132:133], v[150:151] op_sel:[0,1,0]
	v_pk_fma_f32 v[148:149], v[104:105], v[130:131], v[148:149] op_sel_hi:[1,0,1]
	v_pk_fma_f32 v[150:151], v[104:105], v[134:135], v[150:151] op_sel_hi:[1,0,1]
	v_pk_fma_f32 v[148:149], v[106:107], v[130:131], v[148:149] op_sel:[0,1,0]
	v_pk_fma_f32 v[150:151], v[106:107], v[134:135], v[150:151] op_sel:[0,1,0]
	v_pk_fma_f32 v[100:101], v[144:145], v[140:141], v[100:101] op_sel_hi:[1,0,1]
	v_add_f32_dpp v148, v148, v148 quad_perm:[1,0,3,2] row_mask:0xf bank_mask:0xf bound_ctrl:1
	v_add_f32_dpp v149, v149, v149 quad_perm:[1,0,3,2] row_mask:0xf bank_mask:0xf bound_ctrl:1
	v_pk_fma_f32 v[102:103], v[144:145], v[140:141], v[102:103] op_sel:[0,1,0]
	v_pk_fma_f32 v[230:231], v[144:145], v[146:147], v[150:151] op_sel_hi:[1,0,1]
	v_add_f32_dpp v148, v148, v148 quad_perm:[2,3,0,1] row_mask:0xf bank_mask:0xf bound_ctrl:1
	v_add_f32_dpp v149, v149, v149 quad_perm:[2,3,0,1] row_mask:0xf bank_mask:0xf bound_ctrl:1
	v_pk_fma_f32 v[104:105], v[144:145], v[142:143], v[104:105] op_sel_hi:[1,0,1]
	v_pk_fma_f32 v[106:107], v[144:145], v[142:143], v[106:107] op_sel:[0,1,0]
	v_add_f32_dpp v148, v148, v148 row_half_mirror row_mask:0xf bank_mask:0xf bound_ctrl:1
	v_add_f32_dpp v149, v149, v149 row_half_mirror row_mask:0xf bank_mask:0xf bound_ctrl:1
	s_nop 1
	v_add_f32_dpp v148, v148, v148 row_mirror row_mask:0xf bank_mask:0xf bound_ctrl:1
	v_add_f32_dpp v149, v149, v149 row_mirror row_mask:0xf bank_mask:0xf bound_ctrl:1
	v_pk_fma_f32 v[100:101], v[148:149], v[136:137], v[100:101] op_sel_hi:[1,0,1]
	v_pk_fma_f32 v[102:103], v[148:149], v[136:137], v[102:103] op_sel:[0,1,0]
	v_pk_fma_f32 v[104:105], v[148:149], v[138:139], v[104:105] op_sel_hi:[1,0,1]
	v_pk_fma_f32 v[106:107], v[148:149], v[138:139], v[106:107] op_sel:[0,1,0]
	s_waitcnt lgkmcnt(0)
	ds_read_b128 v[128:131], v156 offset:19712
	ds_read_b128 v[132:135], v156 offset:19968
	ds_read_b128 v[140:143], v156 offset:20736
	ds_read_b128 v[144:147], v157 offset:19712
	ds_read_b128 v[136:139], v156 offset:20480
	v_pk_mul_f32 v[148:149], v[100:101], v[108:109] op_sel_hi:[1,0]
	v_pk_mul_f32 v[150:151], v[100:101], v[112:113] op_sel_hi:[1,0]
	v_pk_fma_f32 v[148:149], v[102:103], v[108:109], v[148:149] op_sel:[0,1,0]
	v_pk_fma_f32 v[150:151], v[102:103], v[112:113], v[150:151] op_sel:[0,1,0]
	v_pk_fma_f32 v[148:149], v[104:105], v[110:111], v[148:149] op_sel_hi:[1,0,1]
	v_pk_fma_f32 v[150:151], v[104:105], v[114:115], v[150:151] op_sel_hi:[1,0,1]
	v_pk_fma_f32 v[148:149], v[106:107], v[110:111], v[148:149] op_sel:[0,1,0]
	v_pk_fma_f32 v[150:151], v[106:107], v[114:115], v[150:151] op_sel:[0,1,0]
	v_pk_fma_f32 v[100:101], v[124:125], v[120:121], v[100:101] op_sel_hi:[1,0,1]
	v_add_f32_dpp v148, v148, v148 quad_perm:[1,0,3,2] row_mask:0xf bank_mask:0xf bound_ctrl:1
	v_add_f32_dpp v149, v149, v149 quad_perm:[1,0,3,2] row_mask:0xf bank_mask:0xf bound_ctrl:1
	v_pk_fma_f32 v[102:103], v[124:125], v[120:121], v[102:103] op_sel:[0,1,0]
	v_pk_fma_f32 v[234:235], v[124:125], v[126:127], v[150:151] op_sel_hi:[1,0,1]
	v_add_f32_dpp v148, v148, v148 quad_perm:[2,3,0,1] row_mask:0xf bank_mask:0xf bound_ctrl:1
	v_add_f32_dpp v149, v149, v149 quad_perm:[2,3,0,1] row_mask:0xf bank_mask:0xf bound_ctrl:1
	v_pk_fma_f32 v[104:105], v[124:125], v[122:123], v[104:105] op_sel_hi:[1,0,1]
	v_pk_fma_f32 v[106:107], v[124:125], v[122:123], v[106:107] op_sel:[0,1,0]
	v_add_f32_dpp v148, v148, v148 row_half_mirror row_mask:0xf bank_mask:0xf bound_ctrl:1
	v_add_f32_dpp v149, v149, v149 row_half_mirror row_mask:0xf bank_mask:0xf bound_ctrl:1
	s_nop 1
	v_add_f32_dpp v148, v148, v148 row_mirror row_mask:0xf bank_mask:0xf bound_ctrl:1
	v_add_f32_dpp v149, v149, v149 row_mirror row_mask:0xf bank_mask:0xf bound_ctrl:1
	v_pk_fma_f32 v[100:101], v[148:149], v[116:117], v[100:101] op_sel_hi:[1,0,1]
	v_pk_fma_f32 v[102:103], v[148:149], v[116:117], v[102:103] op_sel:[0,1,0]
	v_pk_fma_f32 v[104:105], v[148:149], v[118:119], v[104:105] op_sel_hi:[1,0,1]
	v_pk_fma_f32 v[106:107], v[148:149], v[118:119], v[106:107] op_sel:[0,1,0]
	s_waitcnt lgkmcnt(0)
	ds_read_b128 v[108:111], v156 offset:21504
	ds_read_b128 v[112:115], v156 offset:21760
	ds_read_b128 v[120:123], v156 offset:22528
	ds_read_b128 v[124:127], v157 offset:21504
	ds_read_b128 v[116:119], v156 offset:22272
	v_pk_mul_f32 v[148:149], v[100:101], v[128:129] op_sel_hi:[1,0]
	v_pk_mul_f32 v[150:151], v[100:101], v[132:133] op_sel_hi:[1,0]
	v_pk_fma_f32 v[148:149], v[102:103], v[128:129], v[148:149] op_sel:[0,1,0]
	v_pk_fma_f32 v[150:151], v[102:103], v[132:133], v[150:151] op_sel:[0,1,0]
	v_pk_fma_f32 v[148:149], v[104:105], v[130:131], v[148:149] op_sel_hi:[1,0,1]
	v_pk_fma_f32 v[150:151], v[104:105], v[134:135], v[150:151] op_sel_hi:[1,0,1]
	v_pk_fma_f32 v[148:149], v[106:107], v[130:131], v[148:149] op_sel:[0,1,0]
	v_pk_fma_f32 v[150:151], v[106:107], v[134:135], v[150:151] op_sel:[0,1,0]
	v_pk_fma_f32 v[100:101], v[144:145], v[140:141], v[100:101] op_sel_hi:[1,0,1]
	v_add_f32_dpp v148, v148, v148 quad_perm:[1,0,3,2] row_mask:0xf bank_mask:0xf bound_ctrl:1
	v_add_f32_dpp v149, v149, v149 quad_perm:[1,0,3,2] row_mask:0xf bank_mask:0xf bound_ctrl:1
	v_pk_fma_f32 v[102:103], v[144:145], v[140:141], v[102:103] op_sel:[0,1,0]
	v_pk_fma_f32 v[236:237], v[144:145], v[146:147], v[150:151] op_sel_hi:[1,0,1]
	v_add_f32_dpp v148, v148, v148 quad_perm:[2,3,0,1] row_mask:0xf bank_mask:0xf bound_ctrl:1
	v_add_f32_dpp v149, v149, v149 quad_perm:[2,3,0,1] row_mask:0xf bank_mask:0xf bound_ctrl:1
	v_pk_fma_f32 v[104:105], v[144:145], v[142:143], v[104:105] op_sel_hi:[1,0,1]
	v_pk_fma_f32 v[106:107], v[144:145], v[142:143], v[106:107] op_sel:[0,1,0]
	v_add_f32_dpp v148, v148, v148 row_half_mirror row_mask:0xf bank_mask:0xf bound_ctrl:1
	v_add_f32_dpp v149, v149, v149 row_half_mirror row_mask:0xf bank_mask:0xf bound_ctrl:1
	s_nop 1
	v_add_f32_dpp v148, v148, v148 row_mirror row_mask:0xf bank_mask:0xf bound_ctrl:1
	v_add_f32_dpp v149, v149, v149 row_mirror row_mask:0xf bank_mask:0xf bound_ctrl:1
	v_pk_fma_f32 v[100:101], v[148:149], v[136:137], v[100:101] op_sel_hi:[1,0,1]
	v_pk_fma_f32 v[102:103], v[148:149], v[136:137], v[102:103] op_sel:[0,1,0]
	v_pk_fma_f32 v[104:105], v[148:149], v[138:139], v[104:105] op_sel_hi:[1,0,1]
	v_pk_fma_f32 v[106:107], v[148:149], v[138:139], v[106:107] op_sel:[0,1,0]
	s_waitcnt lgkmcnt(0)
	ds_read_b128 v[128:131], v156 offset:23296
	ds_read_b128 v[132:135], v156 offset:23552
	ds_read_b128 v[140:143], v156 offset:24320
	ds_read_b128 v[144:147], v157 offset:23296
	ds_read_b128 v[136:139], v156 offset:24064
	v_pk_mul_f32 v[148:149], v[100:101], v[108:109] op_sel_hi:[1,0]
	v_pk_mul_f32 v[150:151], v[100:101], v[112:113] op_sel_hi:[1,0]
	v_pk_fma_f32 v[148:149], v[102:103], v[108:109], v[148:149] op_sel:[0,1,0]
	v_pk_fma_f32 v[150:151], v[102:103], v[112:113], v[150:151] op_sel:[0,1,0]
	v_pk_fma_f32 v[148:149], v[104:105], v[110:111], v[148:149] op_sel_hi:[1,0,1]
	v_pk_fma_f32 v[150:151], v[104:105], v[114:115], v[150:151] op_sel_hi:[1,0,1]
	v_pk_fma_f32 v[148:149], v[106:107], v[110:111], v[148:149] op_sel:[0,1,0]
	v_pk_fma_f32 v[150:151], v[106:107], v[114:115], v[150:151] op_sel:[0,1,0]
	v_pk_fma_f32 v[100:101], v[124:125], v[120:121], v[100:101] op_sel_hi:[1,0,1]
	v_add_f32_dpp v148, v148, v148 quad_perm:[1,0,3,2] row_mask:0xf bank_mask:0xf bound_ctrl:1
	v_add_f32_dpp v149, v149, v149 quad_perm:[1,0,3,2] row_mask:0xf bank_mask:0xf bound_ctrl:1
	v_pk_fma_f32 v[102:103], v[124:125], v[120:121], v[102:103] op_sel:[0,1,0]
	v_pk_fma_f32 v[238:239], v[124:125], v[126:127], v[150:151] op_sel_hi:[1,0,1]
	v_add_f32_dpp v148, v148, v148 quad_perm:[2,3,0,1] row_mask:0xf bank_mask:0xf bound_ctrl:1
	v_add_f32_dpp v149, v149, v149 quad_perm:[2,3,0,1] row_mask:0xf bank_mask:0xf bound_ctrl:1
	v_pk_fma_f32 v[104:105], v[124:125], v[122:123], v[104:105] op_sel_hi:[1,0,1]
	v_pk_fma_f32 v[106:107], v[124:125], v[122:123], v[106:107] op_sel:[0,1,0]
	v_add_f32_dpp v148, v148, v148 row_half_mirror row_mask:0xf bank_mask:0xf bound_ctrl:1
	v_add_f32_dpp v149, v149, v149 row_half_mirror row_mask:0xf bank_mask:0xf bound_ctrl:1
	s_nop 1
	v_add_f32_dpp v148, v148, v148 row_mirror row_mask:0xf bank_mask:0xf bound_ctrl:1
	v_add_f32_dpp v149, v149, v149 row_mirror row_mask:0xf bank_mask:0xf bound_ctrl:1
	v_pk_fma_f32 v[100:101], v[148:149], v[116:117], v[100:101] op_sel_hi:[1,0,1]
	v_pk_fma_f32 v[102:103], v[148:149], v[116:117], v[102:103] op_sel:[0,1,0]
	v_pk_fma_f32 v[104:105], v[148:149], v[118:119], v[104:105] op_sel_hi:[1,0,1]
	v_pk_fma_f32 v[106:107], v[148:149], v[118:119], v[106:107] op_sel:[0,1,0]
	s_waitcnt lgkmcnt(0)
	ds_read_b128 v[108:111], v156 offset:25088
	ds_read_b128 v[112:115], v156 offset:25344
	ds_read_b128 v[120:123], v156 offset:26112
	ds_read_b128 v[124:127], v157 offset:25088
	ds_read_b128 v[116:119], v156 offset:25856
	v_pk_mul_f32 v[148:149], v[100:101], v[128:129] op_sel_hi:[1,0]
	v_pk_mul_f32 v[150:151], v[100:101], v[132:133] op_sel_hi:[1,0]
	v_pk_fma_f32 v[148:149], v[102:103], v[128:129], v[148:149] op_sel:[0,1,0]
	v_pk_fma_f32 v[150:151], v[102:103], v[132:133], v[150:151] op_sel:[0,1,0]
	v_pk_fma_f32 v[148:149], v[104:105], v[130:131], v[148:149] op_sel_hi:[1,0,1]
	v_pk_fma_f32 v[150:151], v[104:105], v[134:135], v[150:151] op_sel_hi:[1,0,1]
	v_pk_fma_f32 v[148:149], v[106:107], v[130:131], v[148:149] op_sel:[0,1,0]
	v_pk_fma_f32 v[150:151], v[106:107], v[134:135], v[150:151] op_sel:[0,1,0]
	v_pk_fma_f32 v[100:101], v[144:145], v[140:141], v[100:101] op_sel_hi:[1,0,1]
	v_add_f32_dpp v148, v148, v148 quad_perm:[1,0,3,2] row_mask:0xf bank_mask:0xf bound_ctrl:1
	v_add_f32_dpp v149, v149, v149 quad_perm:[1,0,3,2] row_mask:0xf bank_mask:0xf bound_ctrl:1
	v_pk_fma_f32 v[102:103], v[144:145], v[140:141], v[102:103] op_sel:[0,1,0]
	v_pk_fma_f32 v[240:241], v[144:145], v[146:147], v[150:151] op_sel_hi:[1,0,1]
	v_add_f32_dpp v148, v148, v148 quad_perm:[2,3,0,1] row_mask:0xf bank_mask:0xf bound_ctrl:1
	v_add_f32_dpp v149, v149, v149 quad_perm:[2,3,0,1] row_mask:0xf bank_mask:0xf bound_ctrl:1
	v_pk_fma_f32 v[104:105], v[144:145], v[142:143], v[104:105] op_sel_hi:[1,0,1]
	v_pk_fma_f32 v[106:107], v[144:145], v[142:143], v[106:107] op_sel:[0,1,0]
	v_add_f32_dpp v148, v148, v148 row_half_mirror row_mask:0xf bank_mask:0xf bound_ctrl:1
	v_add_f32_dpp v149, v149, v149 row_half_mirror row_mask:0xf bank_mask:0xf bound_ctrl:1
	s_nop 1
	v_add_f32_dpp v148, v148, v148 row_mirror row_mask:0xf bank_mask:0xf bound_ctrl:1
	v_add_f32_dpp v149, v149, v149 row_mirror row_mask:0xf bank_mask:0xf bound_ctrl:1
	v_pk_fma_f32 v[100:101], v[148:149], v[136:137], v[100:101] op_sel_hi:[1,0,1]
	v_pk_fma_f32 v[102:103], v[148:149], v[136:137], v[102:103] op_sel:[0,1,0]
	v_pk_fma_f32 v[104:105], v[148:149], v[138:139], v[104:105] op_sel_hi:[1,0,1]
	v_pk_fma_f32 v[106:107], v[148:149], v[138:139], v[106:107] op_sel:[0,1,0]
	s_waitcnt lgkmcnt(0)
	ds_read_b128 v[128:131], v156 offset:26880
	ds_read_b128 v[132:135], v156 offset:27136
	ds_read_b128 v[140:143], v156 offset:27904
	ds_read_b128 v[144:147], v157 offset:26880
	ds_read_b128 v[136:139], v156 offset:27648
	v_pk_mul_f32 v[148:149], v[100:101], v[108:109] op_sel_hi:[1,0]
	v_pk_mul_f32 v[150:151], v[100:101], v[112:113] op_sel_hi:[1,0]
	v_pk_fma_f32 v[148:149], v[102:103], v[108:109], v[148:149] op_sel:[0,1,0]
	v_pk_fma_f32 v[150:151], v[102:103], v[112:113], v[150:151] op_sel:[0,1,0]
	v_pk_fma_f32 v[148:149], v[104:105], v[110:111], v[148:149] op_sel_hi:[1,0,1]
	v_pk_fma_f32 v[150:151], v[104:105], v[114:115], v[150:151] op_sel_hi:[1,0,1]
	v_pk_fma_f32 v[148:149], v[106:107], v[110:111], v[148:149] op_sel:[0,1,0]
	v_pk_fma_f32 v[150:151], v[106:107], v[114:115], v[150:151] op_sel:[0,1,0]
	v_pk_fma_f32 v[100:101], v[124:125], v[120:121], v[100:101] op_sel_hi:[1,0,1]
	v_add_f32_dpp v148, v148, v148 quad_perm:[1,0,3,2] row_mask:0xf bank_mask:0xf bound_ctrl:1
	v_add_f32_dpp v149, v149, v149 quad_perm:[1,0,3,2] row_mask:0xf bank_mask:0xf bound_ctrl:1
	v_pk_fma_f32 v[102:103], v[124:125], v[120:121], v[102:103] op_sel:[0,1,0]
	v_pk_fma_f32 v[242:243], v[124:125], v[126:127], v[150:151] op_sel_hi:[1,0,1]
	v_add_f32_dpp v148, v148, v148 quad_perm:[2,3,0,1] row_mask:0xf bank_mask:0xf bound_ctrl:1
	v_add_f32_dpp v149, v149, v149 quad_perm:[2,3,0,1] row_mask:0xf bank_mask:0xf bound_ctrl:1
	v_pk_fma_f32 v[104:105], v[124:125], v[122:123], v[104:105] op_sel_hi:[1,0,1]
	v_pk_fma_f32 v[106:107], v[124:125], v[122:123], v[106:107] op_sel:[0,1,0]
	v_add_f32_dpp v148, v148, v148 row_half_mirror row_mask:0xf bank_mask:0xf bound_ctrl:1
	v_add_f32_dpp v149, v149, v149 row_half_mirror row_mask:0xf bank_mask:0xf bound_ctrl:1
	s_nop 1
	v_add_f32_dpp v148, v148, v148 row_mirror row_mask:0xf bank_mask:0xf bound_ctrl:1
	v_add_f32_dpp v149, v149, v149 row_mirror row_mask:0xf bank_mask:0xf bound_ctrl:1
	v_pk_fma_f32 v[100:101], v[148:149], v[116:117], v[100:101] op_sel_hi:[1,0,1]
	v_pk_fma_f32 v[102:103], v[148:149], v[116:117], v[102:103] op_sel:[0,1,0]
	v_pk_fma_f32 v[104:105], v[148:149], v[118:119], v[104:105] op_sel_hi:[1,0,1]
	v_pk_fma_f32 v[106:107], v[148:149], v[118:119], v[106:107] op_sel:[0,1,0]
	s_waitcnt lgkmcnt(0)
	ds_read_b128 v[108:111], v156 offset:28672
	ds_read_b128 v[112:115], v156 offset:28928
	ds_read_b128 v[120:123], v156 offset:29696
	ds_read_b128 v[124:127], v157 offset:28672
	ds_read_b128 v[116:119], v156 offset:29440
	ds_read_b128 v[204:207], v156 offset:27392
	v_pk_mul_f32 v[148:149], v[100:101], v[128:129] op_sel_hi:[1,0]
	v_pk_mul_f32 v[150:151], v[100:101], v[132:133] op_sel_hi:[1,0]
	v_pk_fma_f32 v[148:149], v[102:103], v[128:129], v[148:149] op_sel:[0,1,0]
	v_pk_fma_f32 v[150:151], v[102:103], v[132:133], v[150:151] op_sel:[0,1,0]
	v_pk_fma_f32 v[148:149], v[104:105], v[130:131], v[148:149] op_sel_hi:[1,0,1]
	v_pk_fma_f32 v[150:151], v[104:105], v[134:135], v[150:151] op_sel_hi:[1,0,1]
	v_pk_fma_f32 v[148:149], v[106:107], v[130:131], v[148:149] op_sel:[0,1,0]
	v_pk_fma_f32 v[150:151], v[106:107], v[134:135], v[150:151] op_sel:[0,1,0]
	v_pk_fma_f32 v[100:101], v[144:145], v[140:141], v[100:101] op_sel_hi:[1,0,1]
	v_add_f32_dpp v148, v148, v148 quad_perm:[1,0,3,2] row_mask:0xf bank_mask:0xf bound_ctrl:1
	v_add_f32_dpp v149, v149, v149 quad_perm:[1,0,3,2] row_mask:0xf bank_mask:0xf bound_ctrl:1
	v_pk_fma_f32 v[102:103], v[144:145], v[140:141], v[102:103] op_sel:[0,1,0]
	v_pk_fma_f32 v[244:245], v[144:145], v[146:147], v[150:151] op_sel_hi:[1,0,1]
	v_add_f32_dpp v148, v148, v148 quad_perm:[2,3,0,1] row_mask:0xf bank_mask:0xf bound_ctrl:1
	v_add_f32_dpp v149, v149, v149 quad_perm:[2,3,0,1] row_mask:0xf bank_mask:0xf bound_ctrl:1
	v_pk_fma_f32 v[104:105], v[144:145], v[142:143], v[104:105] op_sel_hi:[1,0,1]
	v_pk_fma_f32 v[106:107], v[144:145], v[142:143], v[106:107] op_sel:[0,1,0]
	v_add_f32_dpp v148, v148, v148 row_half_mirror row_mask:0xf bank_mask:0xf bound_ctrl:1
	v_add_f32_dpp v149, v149, v149 row_half_mirror row_mask:0xf bank_mask:0xf bound_ctrl:1
	s_nop 1
	v_add_f32_dpp v148, v148, v148 row_mirror row_mask:0xf bank_mask:0xf bound_ctrl:1
	v_add_f32_dpp v149, v149, v149 row_mirror row_mask:0xf bank_mask:0xf bound_ctrl:1
	v_pk_fma_f32 v[100:101], v[148:149], v[136:137], v[100:101] op_sel_hi:[1,0,1]
	v_pk_fma_f32 v[102:103], v[148:149], v[136:137], v[102:103] op_sel:[0,1,0]
	v_pk_fma_f32 v[104:105], v[148:149], v[138:139], v[104:105] op_sel_hi:[1,0,1]
	v_pk_fma_f32 v[106:107], v[148:149], v[138:139], v[106:107] op_sel:[0,1,0]
	v_add_f32_dpp v212, v212, v212 row_mirror row_mask:0xf bank_mask:0x3
	v_add_f32_dpp v213, v213, v213 row_mirror row_mask:0xf bank_mask:0x3
	v_add_f32_dpp v212, v228, v228 row_mirror row_mask:0xf bank_mask:0xc
	v_add_f32_dpp v213, v229, v229 row_mirror row_mask:0xf bank_mask:0xc
	v_add_f32_dpp v214, v214, v214 row_mirror row_mask:0xf bank_mask:0x3
	v_add_f32_dpp v215, v215, v215 row_mirror row_mask:0xf bank_mask:0x3
	v_add_f32_dpp v214, v230, v230 row_mirror row_mask:0xf bank_mask:0xc
	v_add_f32_dpp v215, v231, v231 row_mirror row_mask:0xf bank_mask:0xc
	v_add_f32_dpp v216, v216, v216 row_mirror row_mask:0xf bank_mask:0x3
	v_add_f32_dpp v217, v217, v217 row_mirror row_mask:0xf bank_mask:0x3
	v_add_f32_dpp v216, v234, v234 row_mirror row_mask:0xf bank_mask:0xc
	v_add_f32_dpp v217, v235, v235 row_mirror row_mask:0xf bank_mask:0xc
	v_add_f32_dpp v218, v218, v218 row_mirror row_mask:0xf bank_mask:0x3
	v_add_f32_dpp v219, v219, v219 row_mirror row_mask:0xf bank_mask:0x3
	v_add_f32_dpp v218, v236, v236 row_mirror row_mask:0xf bank_mask:0xc
	v_add_f32_dpp v219, v237, v237 row_mirror row_mask:0xf bank_mask:0xc
	v_add_f32_dpp v220, v220, v220 row_mirror row_mask:0xf bank_mask:0x3
	v_add_f32_dpp v221, v221, v221 row_mirror row_mask:0xf bank_mask:0x3
	v_add_f32_dpp v220, v238, v238 row_mirror row_mask:0xf bank_mask:0xc
	v_add_f32_dpp v221, v239, v239 row_mirror row_mask:0xf bank_mask:0xc
	v_add_f32_dpp v222, v222, v222 row_mirror row_mask:0xf bank_mask:0x3
	v_add_f32_dpp v223, v223, v223 row_mirror row_mask:0xf bank_mask:0x3
	v_add_f32_dpp v222, v240, v240 row_mirror row_mask:0xf bank_mask:0xc
	v_add_f32_dpp v223, v241, v241 row_mirror row_mask:0xf bank_mask:0xc
	v_add_f32_dpp v224, v224, v224 row_mirror row_mask:0xf bank_mask:0x3
	v_add_f32_dpp v225, v225, v225 row_mirror row_mask:0xf bank_mask:0x3
	v_add_f32_dpp v224, v242, v242 row_mirror row_mask:0xf bank_mask:0xc
	v_add_f32_dpp v225, v243, v243 row_mirror row_mask:0xf bank_mask:0xc
	v_add_f32_dpp v226, v226, v226 row_mirror row_mask:0xf bank_mask:0x3
	v_add_f32_dpp v227, v227, v227 row_mirror row_mask:0xf bank_mask:0x3
	v_add_f32_dpp v226, v244, v244 row_mirror row_mask:0xf bank_mask:0xc
	v_add_f32_dpp v227, v245, v245 row_mirror row_mask:0xf bank_mask:0xc
	v_add_f32_dpp v212, v212, v212 row_half_mirror row_mask:0xf bank_mask:0x5
	v_add_f32_dpp v213, v213, v213 row_half_mirror row_mask:0xf bank_mask:0x5
	v_add_f32_dpp v212, v220, v220 row_half_mirror row_mask:0xf bank_mask:0xa
	v_add_f32_dpp v213, v221, v221 row_half_mirror row_mask:0xf bank_mask:0xa
	v_add_f32_dpp v214, v214, v214 row_half_mirror row_mask:0xf bank_mask:0x5
	v_add_f32_dpp v215, v215, v215 row_half_mirror row_mask:0xf bank_mask:0x5
	v_add_f32_dpp v214, v222, v222 row_half_mirror row_mask:0xf bank_mask:0xa
	v_add_f32_dpp v215, v223, v223 row_half_mirror row_mask:0xf bank_mask:0xa
	v_add_f32_dpp v216, v216, v216 row_half_mirror row_mask:0xf bank_mask:0x5
	v_add_f32_dpp v217, v217, v217 row_half_mirror row_mask:0xf bank_mask:0x5
	v_add_f32_dpp v216, v224, v224 row_half_mirror row_mask:0xf bank_mask:0xa
	v_add_f32_dpp v217, v225, v225 row_half_mirror row_mask:0xf bank_mask:0xa
	v_add_f32_dpp v218, v218, v218 row_half_mirror row_mask:0xf bank_mask:0x5
	v_add_f32_dpp v219, v219, v219 row_half_mirror row_mask:0xf bank_mask:0x5
	v_add_f32_dpp v218, v226, v226 row_half_mirror row_mask:0xf bank_mask:0xa
	v_add_f32_dpp v219, v227, v227 row_half_mirror row_mask:0xf bank_mask:0xa
	v_add_f32_dpp v212, v212, v212 quad_perm:[1,0,3,2] row_mask:0xf bank_mask:0xf
	v_add_f32_dpp v213, v213, v213 quad_perm:[1,0,3,2] row_mask:0xf bank_mask:0xf
	v_add_f32_dpp v214, v214, v214 quad_perm:[1,0,3,2] row_mask:0xf bank_mask:0xf
	v_add_f32_dpp v215, v215, v215 quad_perm:[1,0,3,2] row_mask:0xf bank_mask:0xf
	v_add_f32_dpp v216, v216, v216 quad_perm:[1,0,3,2] row_mask:0xf bank_mask:0xf
	v_add_f32_dpp v217, v217, v217 quad_perm:[1,0,3,2] row_mask:0xf bank_mask:0xf
	v_add_f32_dpp v218, v218, v218 quad_perm:[1,0,3,2] row_mask:0xf bank_mask:0xf
	v_add_f32_dpp v219, v219, v219 quad_perm:[1,0,3,2] row_mask:0xf bank_mask:0xf
	v_add_f32_dpp v212, v212, v212 quad_perm:[2,3,0,1] row_mask:0xf bank_mask:0xf
	v_add_f32_dpp v213, v213, v213 quad_perm:[2,3,0,1] row_mask:0xf bank_mask:0xf
	v_add_f32_dpp v214, v214, v214 quad_perm:[2,3,0,1] row_mask:0xf bank_mask:0xf
	v_add_f32_dpp v215, v215, v215 quad_perm:[2,3,0,1] row_mask:0xf bank_mask:0xf
	v_add_f32_dpp v216, v216, v216 quad_perm:[2,3,0,1] row_mask:0xf bank_mask:0xf
	v_add_f32_dpp v217, v217, v217 quad_perm:[2,3,0,1] row_mask:0xf bank_mask:0xf
	v_add_f32_dpp v218, v218, v218 quad_perm:[2,3,0,1] row_mask:0xf bank_mask:0xf
	v_add_f32_dpp v219, v219, v219 quad_perm:[2,3,0,1] row_mask:0xf bank_mask:0xf
	v_cndmask_b32_e64 v212, v212, v214, s[52:53]
	v_cndmask_b32_e64 v213, v213, v215, s[52:53]
	v_cndmask_b32_e64 v212, v212, v216, s[54:55]
	v_cndmask_b32_e64 v213, v213, v217, s[54:55]
	v_cndmask_b32_e64 v212, v212, v218, vcc
	v_cndmask_b32_e64 v213, v213, v219, vcc
	v_cvt_pk_bf16_f32 v155, v212, v213
	global_store_dword v[160:161], v155, off
	v_lshl_add_u64 v[160:161], v[160:161], 0, s[60:61]
	s_waitcnt lgkmcnt(0)
	v_pk_mul_f32 v[100:101], v[100:101], v[204:205] op_sel_hi:[1,0]
	v_pk_mul_f32 v[102:103], v[102:103], v[204:205] op_sel:[0,1]
	v_pk_mul_f32 v[104:105], v[104:105], v[206:207] op_sel_hi:[1,0]
	v_pk_mul_f32 v[106:107], v[106:107], v[206:207] op_sel:[0,1]
	ds_read_b128 v[128:131], v156 offset:30464
	ds_read_b128 v[132:135], v156 offset:30720
	ds_read_b128 v[140:143], v156 offset:31488
	ds_read_b128 v[144:147], v157 offset:30464
	ds_read_b128 v[136:139], v156 offset:31232
	v_pk_mul_f32 v[148:149], v[100:101], v[108:109] op_sel_hi:[1,0]
	v_pk_mul_f32 v[150:151], v[100:101], v[112:113] op_sel_hi:[1,0]
	v_pk_fma_f32 v[148:149], v[102:103], v[108:109], v[148:149] op_sel:[0,1,0]
	v_pk_fma_f32 v[150:151], v[102:103], v[112:113], v[150:151] op_sel:[0,1,0]
	v_pk_fma_f32 v[148:149], v[104:105], v[110:111], v[148:149] op_sel_hi:[1,0,1]
	v_pk_fma_f32 v[150:151], v[104:105], v[114:115], v[150:151] op_sel_hi:[1,0,1]
	v_pk_fma_f32 v[148:149], v[106:107], v[110:111], v[148:149] op_sel:[0,1,0]
	v_pk_fma_f32 v[150:151], v[106:107], v[114:115], v[150:151] op_sel:[0,1,0]
	v_pk_fma_f32 v[100:101], v[124:125], v[120:121], v[100:101] op_sel_hi:[1,0,1]
	v_add_f32_dpp v148, v148, v148 quad_perm:[1,0,3,2] row_mask:0xf bank_mask:0xf bound_ctrl:1
	v_add_f32_dpp v149, v149, v149 quad_perm:[1,0,3,2] row_mask:0xf bank_mask:0xf bound_ctrl:1
	v_pk_fma_f32 v[102:103], v[124:125], v[120:121], v[102:103] op_sel:[0,1,0]
	v_pk_fma_f32 v[212:213], v[124:125], v[126:127], v[150:151] op_sel_hi:[1,0,1]
	v_add_f32_dpp v148, v148, v148 quad_perm:[2,3,0,1] row_mask:0xf bank_mask:0xf bound_ctrl:1
	v_add_f32_dpp v149, v149, v149 quad_perm:[2,3,0,1] row_mask:0xf bank_mask:0xf bound_ctrl:1
	v_pk_fma_f32 v[104:105], v[124:125], v[122:123], v[104:105] op_sel_hi:[1,0,1]
	v_pk_fma_f32 v[106:107], v[124:125], v[122:123], v[106:107] op_sel:[0,1,0]
	v_add_f32_dpp v148, v148, v148 row_half_mirror row_mask:0xf bank_mask:0xf bound_ctrl:1
	v_add_f32_dpp v149, v149, v149 row_half_mirror row_mask:0xf bank_mask:0xf bound_ctrl:1
	s_nop 1
	v_add_f32_dpp v148, v148, v148 row_mirror row_mask:0xf bank_mask:0xf bound_ctrl:1
	v_add_f32_dpp v149, v149, v149 row_mirror row_mask:0xf bank_mask:0xf bound_ctrl:1
	v_pk_fma_f32 v[100:101], v[148:149], v[116:117], v[100:101] op_sel_hi:[1,0,1]
	v_pk_fma_f32 v[102:103], v[148:149], v[116:117], v[102:103] op_sel:[0,1,0]
	v_pk_fma_f32 v[104:105], v[148:149], v[118:119], v[104:105] op_sel_hi:[1,0,1]
	v_pk_fma_f32 v[106:107], v[148:149], v[118:119], v[106:107] op_sel:[0,1,0]
	s_waitcnt lgkmcnt(0)
	ds_read_b128 v[108:111], v156 offset:32256
	ds_read_b128 v[112:115], v156 offset:32512
	ds_read_b128 v[120:123], v156 offset:33280
	ds_read_b128 v[124:127], v157 offset:32256
	ds_read_b128 v[116:119], v156 offset:33024
	v_pk_mul_f32 v[148:149], v[100:101], v[128:129] op_sel_hi:[1,0]
	v_pk_mul_f32 v[150:151], v[100:101], v[132:133] op_sel_hi:[1,0]
	v_pk_fma_f32 v[148:149], v[102:103], v[128:129], v[148:149] op_sel:[0,1,0]
	v_pk_fma_f32 v[150:151], v[102:103], v[132:133], v[150:151] op_sel:[0,1,0]
	v_pk_fma_f32 v[148:149], v[104:105], v[130:131], v[148:149] op_sel_hi:[1,0,1]
	v_pk_fma_f32 v[150:151], v[104:105], v[134:135], v[150:151] op_sel_hi:[1,0,1]
	v_pk_fma_f32 v[148:149], v[106:107], v[130:131], v[148:149] op_sel:[0,1,0]
	v_pk_fma_f32 v[150:151], v[106:107], v[134:135], v[150:151] op_sel:[0,1,0]
	v_pk_fma_f32 v[100:101], v[144:145], v[140:141], v[100:101] op_sel_hi:[1,0,1]
	v_add_f32_dpp v148, v148, v148 quad_perm:[1,0,3,2] row_mask:0xf bank_mask:0xf bound_ctrl:1
	v_add_f32_dpp v149, v149, v149 quad_perm:[1,0,3,2] row_mask:0xf bank_mask:0xf bound_ctrl:1
	v_pk_fma_f32 v[102:103], v[144:145], v[140:141], v[102:103] op_sel:[0,1,0]
	v_pk_fma_f32 v[214:215], v[144:145], v[146:147], v[150:151] op_sel_hi:[1,0,1]
	v_add_f32_dpp v148, v148, v148 quad_perm:[2,3,0,1] row_mask:0xf bank_mask:0xf bound_ctrl:1
	v_add_f32_dpp v149, v149, v149 quad_perm:[2,3,0,1] row_mask:0xf bank_mask:0xf bound_ctrl:1
	v_pk_fma_f32 v[104:105], v[144:145], v[142:143], v[104:105] op_sel_hi:[1,0,1]
	v_pk_fma_f32 v[106:107], v[144:145], v[142:143], v[106:107] op_sel:[0,1,0]
	v_add_f32_dpp v148, v148, v148 row_half_mirror row_mask:0xf bank_mask:0xf bound_ctrl:1
	v_add_f32_dpp v149, v149, v149 row_half_mirror row_mask:0xf bank_mask:0xf bound_ctrl:1
	s_nop 1
	v_add_f32_dpp v148, v148, v148 row_mirror row_mask:0xf bank_mask:0xf bound_ctrl:1
	v_add_f32_dpp v149, v149, v149 row_mirror row_mask:0xf bank_mask:0xf bound_ctrl:1
	v_pk_fma_f32 v[100:101], v[148:149], v[136:137], v[100:101] op_sel_hi:[1,0,1]
	v_pk_fma_f32 v[102:103], v[148:149], v[136:137], v[102:103] op_sel:[0,1,0]
	v_pk_fma_f32 v[104:105], v[148:149], v[138:139], v[104:105] op_sel_hi:[1,0,1]
	v_pk_fma_f32 v[106:107], v[148:149], v[138:139], v[106:107] op_sel:[0,1,0]
	s_waitcnt lgkmcnt(0)
	ds_read_b128 v[128:131], v156 offset:34048
	ds_read_b128 v[132:135], v156 offset:34304
	ds_read_b128 v[140:143], v156 offset:35072
	ds_read_b128 v[144:147], v157 offset:34048
	ds_read_b128 v[136:139], v156 offset:34816
	v_pk_mul_f32 v[148:149], v[100:101], v[108:109] op_sel_hi:[1,0]
	v_pk_mul_f32 v[150:151], v[100:101], v[112:113] op_sel_hi:[1,0]
	v_pk_fma_f32 v[148:149], v[102:103], v[108:109], v[148:149] op_sel:[0,1,0]
	v_pk_fma_f32 v[150:151], v[102:103], v[112:113], v[150:151] op_sel:[0,1,0]
	v_pk_fma_f32 v[148:149], v[104:105], v[110:111], v[148:149] op_sel_hi:[1,0,1]
	v_pk_fma_f32 v[150:151], v[104:105], v[114:115], v[150:151] op_sel_hi:[1,0,1]
	v_pk_fma_f32 v[148:149], v[106:107], v[110:111], v[148:149] op_sel:[0,1,0]
	v_pk_fma_f32 v[150:151], v[106:107], v[114:115], v[150:151] op_sel:[0,1,0]
	v_pk_fma_f32 v[100:101], v[124:125], v[120:121], v[100:101] op_sel_hi:[1,0,1]
	v_add_f32_dpp v148, v148, v148 quad_perm:[1,0,3,2] row_mask:0xf bank_mask:0xf bound_ctrl:1
	v_add_f32_dpp v149, v149, v149 quad_perm:[1,0,3,2] row_mask:0xf bank_mask:0xf bound_ctrl:1
	v_pk_fma_f32 v[102:103], v[124:125], v[120:121], v[102:103] op_sel:[0,1,0]
	v_pk_fma_f32 v[216:217], v[124:125], v[126:127], v[150:151] op_sel_hi:[1,0,1]
	v_add_f32_dpp v148, v148, v148 quad_perm:[2,3,0,1] row_mask:0xf bank_mask:0xf bound_ctrl:1
	v_add_f32_dpp v149, v149, v149 quad_perm:[2,3,0,1] row_mask:0xf bank_mask:0xf bound_ctrl:1
	v_pk_fma_f32 v[104:105], v[124:125], v[122:123], v[104:105] op_sel_hi:[1,0,1]
	v_pk_fma_f32 v[106:107], v[124:125], v[122:123], v[106:107] op_sel:[0,1,0]
	v_add_f32_dpp v148, v148, v148 row_half_mirror row_mask:0xf bank_mask:0xf bound_ctrl:1
	v_add_f32_dpp v149, v149, v149 row_half_mirror row_mask:0xf bank_mask:0xf bound_ctrl:1
	s_nop 1
	v_add_f32_dpp v148, v148, v148 row_mirror row_mask:0xf bank_mask:0xf bound_ctrl:1
	v_add_f32_dpp v149, v149, v149 row_mirror row_mask:0xf bank_mask:0xf bound_ctrl:1
	v_pk_fma_f32 v[100:101], v[148:149], v[116:117], v[100:101] op_sel_hi:[1,0,1]
	v_pk_fma_f32 v[102:103], v[148:149], v[116:117], v[102:103] op_sel:[0,1,0]
	v_pk_fma_f32 v[104:105], v[148:149], v[118:119], v[104:105] op_sel_hi:[1,0,1]
	v_pk_fma_f32 v[106:107], v[148:149], v[118:119], v[106:107] op_sel:[0,1,0]
	s_waitcnt lgkmcnt(0)
	ds_read_b128 v[108:111], v156 offset:35840
	ds_read_b128 v[112:115], v156 offset:36096
	ds_read_b128 v[120:123], v156 offset:36864
	ds_read_b128 v[124:127], v157 offset:35840
	ds_read_b128 v[116:119], v156 offset:36608
	v_pk_mul_f32 v[148:149], v[100:101], v[128:129] op_sel_hi:[1,0]
	v_pk_mul_f32 v[150:151], v[100:101], v[132:133] op_sel_hi:[1,0]
	v_pk_fma_f32 v[148:149], v[102:103], v[128:129], v[148:149] op_sel:[0,1,0]
	v_pk_fma_f32 v[150:151], v[102:103], v[132:133], v[150:151] op_sel:[0,1,0]
	v_pk_fma_f32 v[148:149], v[104:105], v[130:131], v[148:149] op_sel_hi:[1,0,1]
	v_pk_fma_f32 v[150:151], v[104:105], v[134:135], v[150:151] op_sel_hi:[1,0,1]
	v_pk_fma_f32 v[148:149], v[106:107], v[130:131], v[148:149] op_sel:[0,1,0]
	v_pk_fma_f32 v[150:151], v[106:107], v[134:135], v[150:151] op_sel:[0,1,0]
	v_pk_fma_f32 v[100:101], v[144:145], v[140:141], v[100:101] op_sel_hi:[1,0,1]
	v_add_f32_dpp v148, v148, v148 quad_perm:[1,0,3,2] row_mask:0xf bank_mask:0xf bound_ctrl:1
	v_add_f32_dpp v149, v149, v149 quad_perm:[1,0,3,2] row_mask:0xf bank_mask:0xf bound_ctrl:1
	v_pk_fma_f32 v[102:103], v[144:145], v[140:141], v[102:103] op_sel:[0,1,0]
	v_pk_fma_f32 v[218:219], v[144:145], v[146:147], v[150:151] op_sel_hi:[1,0,1]
	v_add_f32_dpp v148, v148, v148 quad_perm:[2,3,0,1] row_mask:0xf bank_mask:0xf bound_ctrl:1
	v_add_f32_dpp v149, v149, v149 quad_perm:[2,3,0,1] row_mask:0xf bank_mask:0xf bound_ctrl:1
	v_pk_fma_f32 v[104:105], v[144:145], v[142:143], v[104:105] op_sel_hi:[1,0,1]
	v_pk_fma_f32 v[106:107], v[144:145], v[142:143], v[106:107] op_sel:[0,1,0]
	v_add_f32_dpp v148, v148, v148 row_half_mirror row_mask:0xf bank_mask:0xf bound_ctrl:1
	v_add_f32_dpp v149, v149, v149 row_half_mirror row_mask:0xf bank_mask:0xf bound_ctrl:1
	s_nop 1
	v_add_f32_dpp v148, v148, v148 row_mirror row_mask:0xf bank_mask:0xf bound_ctrl:1
	v_add_f32_dpp v149, v149, v149 row_mirror row_mask:0xf bank_mask:0xf bound_ctrl:1
	v_pk_fma_f32 v[100:101], v[148:149], v[136:137], v[100:101] op_sel_hi:[1,0,1]
	v_pk_fma_f32 v[102:103], v[148:149], v[136:137], v[102:103] op_sel:[0,1,0]
	v_pk_fma_f32 v[104:105], v[148:149], v[138:139], v[104:105] op_sel_hi:[1,0,1]
	v_pk_fma_f32 v[106:107], v[148:149], v[138:139], v[106:107] op_sel:[0,1,0]
	s_waitcnt lgkmcnt(0)
	ds_read_b128 v[128:131], v156 offset:37632
	ds_read_b128 v[132:135], v156 offset:37888
	ds_read_b128 v[140:143], v156 offset:38656
	ds_read_b128 v[144:147], v157 offset:37632
	ds_read_b128 v[136:139], v156 offset:38400
	v_pk_mul_f32 v[148:149], v[100:101], v[108:109] op_sel_hi:[1,0]
	v_pk_mul_f32 v[150:151], v[100:101], v[112:113] op_sel_hi:[1,0]
	v_pk_fma_f32 v[148:149], v[102:103], v[108:109], v[148:149] op_sel:[0,1,0]
	v_pk_fma_f32 v[150:151], v[102:103], v[112:113], v[150:151] op_sel:[0,1,0]
	v_pk_fma_f32 v[148:149], v[104:105], v[110:111], v[148:149] op_sel_hi:[1,0,1]
	v_pk_fma_f32 v[150:151], v[104:105], v[114:115], v[150:151] op_sel_hi:[1,0,1]
	v_pk_fma_f32 v[148:149], v[106:107], v[110:111], v[148:149] op_sel:[0,1,0]
	v_pk_fma_f32 v[150:151], v[106:107], v[114:115], v[150:151] op_sel:[0,1,0]
	v_pk_fma_f32 v[100:101], v[124:125], v[120:121], v[100:101] op_sel_hi:[1,0,1]
	v_add_f32_dpp v148, v148, v148 quad_perm:[1,0,3,2] row_mask:0xf bank_mask:0xf bound_ctrl:1
	v_add_f32_dpp v149, v149, v149 quad_perm:[1,0,3,2] row_mask:0xf bank_mask:0xf bound_ctrl:1
	v_pk_fma_f32 v[102:103], v[124:125], v[120:121], v[102:103] op_sel:[0,1,0]
	v_pk_fma_f32 v[220:221], v[124:125], v[126:127], v[150:151] op_sel_hi:[1,0,1]
	v_add_f32_dpp v148, v148, v148 quad_perm:[2,3,0,1] row_mask:0xf bank_mask:0xf bound_ctrl:1
	v_add_f32_dpp v149, v149, v149 quad_perm:[2,3,0,1] row_mask:0xf bank_mask:0xf bound_ctrl:1
	v_pk_fma_f32 v[104:105], v[124:125], v[122:123], v[104:105] op_sel_hi:[1,0,1]
	v_pk_fma_f32 v[106:107], v[124:125], v[122:123], v[106:107] op_sel:[0,1,0]
	v_add_f32_dpp v148, v148, v148 row_half_mirror row_mask:0xf bank_mask:0xf bound_ctrl:1
	v_add_f32_dpp v149, v149, v149 row_half_mirror row_mask:0xf bank_mask:0xf bound_ctrl:1
	s_nop 1
	v_add_f32_dpp v148, v148, v148 row_mirror row_mask:0xf bank_mask:0xf bound_ctrl:1
	v_add_f32_dpp v149, v149, v149 row_mirror row_mask:0xf bank_mask:0xf bound_ctrl:1
	v_pk_fma_f32 v[100:101], v[148:149], v[116:117], v[100:101] op_sel_hi:[1,0,1]
	v_pk_fma_f32 v[102:103], v[148:149], v[116:117], v[102:103] op_sel:[0,1,0]
	v_pk_fma_f32 v[104:105], v[148:149], v[118:119], v[104:105] op_sel_hi:[1,0,1]
	v_pk_fma_f32 v[106:107], v[148:149], v[118:119], v[106:107] op_sel:[0,1,0]
	s_waitcnt lgkmcnt(0)
	ds_read_b128 v[108:111], v156 offset:39424
	ds_read_b128 v[112:115], v156 offset:39680
	ds_read_b128 v[120:123], v156 offset:40448
	ds_read_b128 v[124:127], v157 offset:39424
	ds_read_b128 v[116:119], v156 offset:40192
	v_pk_mul_f32 v[148:149], v[100:101], v[128:129] op_sel_hi:[1,0]
	v_pk_mul_f32 v[150:151], v[100:101], v[132:133] op_sel_hi:[1,0]
	v_pk_fma_f32 v[148:149], v[102:103], v[128:129], v[148:149] op_sel:[0,1,0]
	v_pk_fma_f32 v[150:151], v[102:103], v[132:133], v[150:151] op_sel:[0,1,0]
	v_pk_fma_f32 v[148:149], v[104:105], v[130:131], v[148:149] op_sel_hi:[1,0,1]
	v_pk_fma_f32 v[150:151], v[104:105], v[134:135], v[150:151] op_sel_hi:[1,0,1]
	v_pk_fma_f32 v[148:149], v[106:107], v[130:131], v[148:149] op_sel:[0,1,0]
	v_pk_fma_f32 v[150:151], v[106:107], v[134:135], v[150:151] op_sel:[0,1,0]
	v_pk_fma_f32 v[100:101], v[144:145], v[140:141], v[100:101] op_sel_hi:[1,0,1]
	v_add_f32_dpp v148, v148, v148 quad_perm:[1,0,3,2] row_mask:0xf bank_mask:0xf bound_ctrl:1
	v_add_f32_dpp v149, v149, v149 quad_perm:[1,0,3,2] row_mask:0xf bank_mask:0xf bound_ctrl:1
	v_pk_fma_f32 v[102:103], v[144:145], v[140:141], v[102:103] op_sel:[0,1,0]
	v_pk_fma_f32 v[222:223], v[144:145], v[146:147], v[150:151] op_sel_hi:[1,0,1]
	v_add_f32_dpp v148, v148, v148 quad_perm:[2,3,0,1] row_mask:0xf bank_mask:0xf bound_ctrl:1
	v_add_f32_dpp v149, v149, v149 quad_perm:[2,3,0,1] row_mask:0xf bank_mask:0xf bound_ctrl:1
	v_pk_fma_f32 v[104:105], v[144:145], v[142:143], v[104:105] op_sel_hi:[1,0,1]
	v_pk_fma_f32 v[106:107], v[144:145], v[142:143], v[106:107] op_sel:[0,1,0]
	v_add_f32_dpp v148, v148, v148 row_half_mirror row_mask:0xf bank_mask:0xf bound_ctrl:1
	v_add_f32_dpp v149, v149, v149 row_half_mirror row_mask:0xf bank_mask:0xf bound_ctrl:1
	s_nop 1
	v_add_f32_dpp v148, v148, v148 row_mirror row_mask:0xf bank_mask:0xf bound_ctrl:1
	v_add_f32_dpp v149, v149, v149 row_mirror row_mask:0xf bank_mask:0xf bound_ctrl:1
	v_pk_fma_f32 v[100:101], v[148:149], v[136:137], v[100:101] op_sel_hi:[1,0,1]
	v_pk_fma_f32 v[102:103], v[148:149], v[136:137], v[102:103] op_sel:[0,1,0]
	v_pk_fma_f32 v[104:105], v[148:149], v[138:139], v[104:105] op_sel_hi:[1,0,1]
	v_pk_fma_f32 v[106:107], v[148:149], v[138:139], v[106:107] op_sel:[0,1,0]
	s_waitcnt lgkmcnt(0)
	ds_read_b128 v[128:131], v156 offset:41216
	ds_read_b128 v[132:135], v156 offset:41472
	ds_read_b128 v[140:143], v156 offset:42240
	ds_read_b128 v[144:147], v157 offset:41216
	ds_read_b128 v[136:139], v156 offset:41984
	v_pk_mul_f32 v[148:149], v[100:101], v[108:109] op_sel_hi:[1,0]
	v_pk_mul_f32 v[150:151], v[100:101], v[112:113] op_sel_hi:[1,0]
	v_pk_fma_f32 v[148:149], v[102:103], v[108:109], v[148:149] op_sel:[0,1,0]
	v_pk_fma_f32 v[150:151], v[102:103], v[112:113], v[150:151] op_sel:[0,1,0]
	v_pk_fma_f32 v[148:149], v[104:105], v[110:111], v[148:149] op_sel_hi:[1,0,1]
	v_pk_fma_f32 v[150:151], v[104:105], v[114:115], v[150:151] op_sel_hi:[1,0,1]
	v_pk_fma_f32 v[148:149], v[106:107], v[110:111], v[148:149] op_sel:[0,1,0]
	v_pk_fma_f32 v[150:151], v[106:107], v[114:115], v[150:151] op_sel:[0,1,0]
	v_pk_fma_f32 v[100:101], v[124:125], v[120:121], v[100:101] op_sel_hi:[1,0,1]
	v_add_f32_dpp v148, v148, v148 quad_perm:[1,0,3,2] row_mask:0xf bank_mask:0xf bound_ctrl:1
	v_add_f32_dpp v149, v149, v149 quad_perm:[1,0,3,2] row_mask:0xf bank_mask:0xf bound_ctrl:1
	v_pk_fma_f32 v[102:103], v[124:125], v[120:121], v[102:103] op_sel:[0,1,0]
	v_pk_fma_f32 v[224:225], v[124:125], v[126:127], v[150:151] op_sel_hi:[1,0,1]
	v_add_f32_dpp v148, v148, v148 quad_perm:[2,3,0,1] row_mask:0xf bank_mask:0xf bound_ctrl:1
	v_add_f32_dpp v149, v149, v149 quad_perm:[2,3,0,1] row_mask:0xf bank_mask:0xf bound_ctrl:1
	v_pk_fma_f32 v[104:105], v[124:125], v[122:123], v[104:105] op_sel_hi:[1,0,1]
	v_pk_fma_f32 v[106:107], v[124:125], v[122:123], v[106:107] op_sel:[0,1,0]
	v_add_f32_dpp v148, v148, v148 row_half_mirror row_mask:0xf bank_mask:0xf bound_ctrl:1
	v_add_f32_dpp v149, v149, v149 row_half_mirror row_mask:0xf bank_mask:0xf bound_ctrl:1
	s_nop 1
	v_add_f32_dpp v148, v148, v148 row_mirror row_mask:0xf bank_mask:0xf bound_ctrl:1
	v_add_f32_dpp v149, v149, v149 row_mirror row_mask:0xf bank_mask:0xf bound_ctrl:1
	v_pk_fma_f32 v[100:101], v[148:149], v[116:117], v[100:101] op_sel_hi:[1,0,1]
	v_pk_fma_f32 v[102:103], v[148:149], v[116:117], v[102:103] op_sel:[0,1,0]
	v_pk_fma_f32 v[104:105], v[148:149], v[118:119], v[104:105] op_sel_hi:[1,0,1]
	v_pk_fma_f32 v[106:107], v[148:149], v[118:119], v[106:107] op_sel:[0,1,0]
	s_waitcnt lgkmcnt(0)
	ds_read_b128 v[108:111], v156 offset:43008
	ds_read_b128 v[112:115], v156 offset:43264
	ds_read_b128 v[120:123], v156 offset:44032
	ds_read_b128 v[124:127], v157 offset:43008
	ds_read_b128 v[116:119], v156 offset:43776
	ds_read_b128 v[204:207], v156 offset:41728
	v_pk_mul_f32 v[148:149], v[100:101], v[128:129] op_sel_hi:[1,0]
	v_pk_mul_f32 v[150:151], v[100:101], v[132:133] op_sel_hi:[1,0]
	v_pk_fma_f32 v[148:149], v[102:103], v[128:129], v[148:149] op_sel:[0,1,0]
	v_pk_fma_f32 v[150:151], v[102:103], v[132:133], v[150:151] op_sel:[0,1,0]
	v_pk_fma_f32 v[148:149], v[104:105], v[130:131], v[148:149] op_sel_hi:[1,0,1]
	v_pk_fma_f32 v[150:151], v[104:105], v[134:135], v[150:151] op_sel_hi:[1,0,1]
	v_pk_fma_f32 v[148:149], v[106:107], v[130:131], v[148:149] op_sel:[0,1,0]
	v_pk_fma_f32 v[150:151], v[106:107], v[134:135], v[150:151] op_sel:[0,1,0]
	v_pk_fma_f32 v[100:101], v[144:145], v[140:141], v[100:101] op_sel_hi:[1,0,1]
	v_add_f32_dpp v148, v148, v148 quad_perm:[1,0,3,2] row_mask:0xf bank_mask:0xf bound_ctrl:1
	v_add_f32_dpp v149, v149, v149 quad_perm:[1,0,3,2] row_mask:0xf bank_mask:0xf bound_ctrl:1
	v_pk_fma_f32 v[102:103], v[144:145], v[140:141], v[102:103] op_sel:[0,1,0]
	v_pk_fma_f32 v[226:227], v[144:145], v[146:147], v[150:151] op_sel_hi:[1,0,1]
	v_add_f32_dpp v148, v148, v148 quad_perm:[2,3,0,1] row_mask:0xf bank_mask:0xf bound_ctrl:1
	v_add_f32_dpp v149, v149, v149 quad_perm:[2,3,0,1] row_mask:0xf bank_mask:0xf bound_ctrl:1
	v_pk_fma_f32 v[104:105], v[144:145], v[142:143], v[104:105] op_sel_hi:[1,0,1]
	v_pk_fma_f32 v[106:107], v[144:145], v[142:143], v[106:107] op_sel:[0,1,0]
	v_add_f32_dpp v148, v148, v148 row_half_mirror row_mask:0xf bank_mask:0xf bound_ctrl:1
	v_add_f32_dpp v149, v149, v149 row_half_mirror row_mask:0xf bank_mask:0xf bound_ctrl:1
	s_nop 1
	v_add_f32_dpp v148, v148, v148 row_mirror row_mask:0xf bank_mask:0xf bound_ctrl:1
	v_add_f32_dpp v149, v149, v149 row_mirror row_mask:0xf bank_mask:0xf bound_ctrl:1
	v_pk_fma_f32 v[100:101], v[148:149], v[136:137], v[100:101] op_sel_hi:[1,0,1]
	v_pk_fma_f32 v[102:103], v[148:149], v[136:137], v[102:103] op_sel:[0,1,0]
	v_pk_fma_f32 v[104:105], v[148:149], v[138:139], v[104:105] op_sel_hi:[1,0,1]
	v_pk_fma_f32 v[106:107], v[148:149], v[138:139], v[106:107] op_sel:[0,1,0]
	s_waitcnt lgkmcnt(0)
	v_pk_mul_f32 v[100:101], v[100:101], v[204:205] op_sel_hi:[1,0]
	v_pk_mul_f32 v[102:103], v[102:103], v[204:205] op_sel:[0,1]
	v_pk_mul_f32 v[104:105], v[104:105], v[206:207] op_sel_hi:[1,0]
	v_pk_mul_f32 v[106:107], v[106:107], v[206:207] op_sel:[0,1]
	ds_read_b128 v[128:131], v156 offset:44800
	ds_read_b128 v[132:135], v156 offset:45056
	ds_read_b128 v[140:143], v156 offset:45824
	ds_read_b128 v[144:147], v157 offset:44800
	ds_read_b128 v[136:139], v156 offset:45568
	v_pk_mul_f32 v[148:149], v[100:101], v[108:109] op_sel_hi:[1,0]
	v_pk_mul_f32 v[150:151], v[100:101], v[112:113] op_sel_hi:[1,0]
	v_pk_fma_f32 v[148:149], v[102:103], v[108:109], v[148:149] op_sel:[0,1,0]
	v_pk_fma_f32 v[150:151], v[102:103], v[112:113], v[150:151] op_sel:[0,1,0]
	v_pk_fma_f32 v[148:149], v[104:105], v[110:111], v[148:149] op_sel_hi:[1,0,1]
	v_pk_fma_f32 v[150:151], v[104:105], v[114:115], v[150:151] op_sel_hi:[1,0,1]
	v_pk_fma_f32 v[148:149], v[106:107], v[110:111], v[148:149] op_sel:[0,1,0]
	v_pk_fma_f32 v[150:151], v[106:107], v[114:115], v[150:151] op_sel:[0,1,0]
	v_pk_fma_f32 v[100:101], v[124:125], v[120:121], v[100:101] op_sel_hi:[1,0,1]
	v_add_f32_dpp v148, v148, v148 quad_perm:[1,0,3,2] row_mask:0xf bank_mask:0xf bound_ctrl:1
	v_add_f32_dpp v149, v149, v149 quad_perm:[1,0,3,2] row_mask:0xf bank_mask:0xf bound_ctrl:1
	v_pk_fma_f32 v[102:103], v[124:125], v[120:121], v[102:103] op_sel:[0,1,0]
	v_pk_fma_f32 v[228:229], v[124:125], v[126:127], v[150:151] op_sel_hi:[1,0,1]
	v_add_f32_dpp v148, v148, v148 quad_perm:[2,3,0,1] row_mask:0xf bank_mask:0xf bound_ctrl:1
	v_add_f32_dpp v149, v149, v149 quad_perm:[2,3,0,1] row_mask:0xf bank_mask:0xf bound_ctrl:1
	v_pk_fma_f32 v[104:105], v[124:125], v[122:123], v[104:105] op_sel_hi:[1,0,1]
	v_pk_fma_f32 v[106:107], v[124:125], v[122:123], v[106:107] op_sel:[0,1,0]
	v_add_f32_dpp v148, v148, v148 row_half_mirror row_mask:0xf bank_mask:0xf bound_ctrl:1
	v_add_f32_dpp v149, v149, v149 row_half_mirror row_mask:0xf bank_mask:0xf bound_ctrl:1
	s_nop 1
	v_add_f32_dpp v148, v148, v148 row_mirror row_mask:0xf bank_mask:0xf bound_ctrl:1
	v_add_f32_dpp v149, v149, v149 row_mirror row_mask:0xf bank_mask:0xf bound_ctrl:1
	v_pk_fma_f32 v[100:101], v[148:149], v[116:117], v[100:101] op_sel_hi:[1,0,1]
	v_pk_fma_f32 v[102:103], v[148:149], v[116:117], v[102:103] op_sel:[0,1,0]
	v_pk_fma_f32 v[104:105], v[148:149], v[118:119], v[104:105] op_sel_hi:[1,0,1]
	v_pk_fma_f32 v[106:107], v[148:149], v[118:119], v[106:107] op_sel:[0,1,0]
	s_waitcnt lgkmcnt(0)
	ds_read_b128 v[108:111], v156 offset:46592
	ds_read_b128 v[112:115], v156 offset:46848
	ds_read_b128 v[120:123], v156 offset:47616
	ds_read_b128 v[124:127], v157 offset:46592
	ds_read_b128 v[116:119], v156 offset:47360
	v_pk_mul_f32 v[148:149], v[100:101], v[128:129] op_sel_hi:[1,0]
	v_pk_mul_f32 v[150:151], v[100:101], v[132:133] op_sel_hi:[1,0]
	v_pk_fma_f32 v[148:149], v[102:103], v[128:129], v[148:149] op_sel:[0,1,0]
	v_pk_fma_f32 v[150:151], v[102:103], v[132:133], v[150:151] op_sel:[0,1,0]
	v_pk_fma_f32 v[148:149], v[104:105], v[130:131], v[148:149] op_sel_hi:[1,0,1]
	v_pk_fma_f32 v[150:151], v[104:105], v[134:135], v[150:151] op_sel_hi:[1,0,1]
	v_pk_fma_f32 v[148:149], v[106:107], v[130:131], v[148:149] op_sel:[0,1,0]
	v_pk_fma_f32 v[150:151], v[106:107], v[134:135], v[150:151] op_sel:[0,1,0]
	v_pk_fma_f32 v[100:101], v[144:145], v[140:141], v[100:101] op_sel_hi:[1,0,1]
	v_add_f32_dpp v148, v148, v148 quad_perm:[1,0,3,2] row_mask:0xf bank_mask:0xf bound_ctrl:1
	v_add_f32_dpp v149, v149, v149 quad_perm:[1,0,3,2] row_mask:0xf bank_mask:0xf bound_ctrl:1
	v_pk_fma_f32 v[102:103], v[144:145], v[140:141], v[102:103] op_sel:[0,1,0]
	v_pk_fma_f32 v[230:231], v[144:145], v[146:147], v[150:151] op_sel_hi:[1,0,1]
	v_add_f32_dpp v148, v148, v148 quad_perm:[2,3,0,1] row_mask:0xf bank_mask:0xf bound_ctrl:1
	v_add_f32_dpp v149, v149, v149 quad_perm:[2,3,0,1] row_mask:0xf bank_mask:0xf bound_ctrl:1
	v_pk_fma_f32 v[104:105], v[144:145], v[142:143], v[104:105] op_sel_hi:[1,0,1]
	v_pk_fma_f32 v[106:107], v[144:145], v[142:143], v[106:107] op_sel:[0,1,0]
	v_add_f32_dpp v148, v148, v148 row_half_mirror row_mask:0xf bank_mask:0xf bound_ctrl:1
	v_add_f32_dpp v149, v149, v149 row_half_mirror row_mask:0xf bank_mask:0xf bound_ctrl:1
	s_nop 1
	v_add_f32_dpp v148, v148, v148 row_mirror row_mask:0xf bank_mask:0xf bound_ctrl:1
	v_add_f32_dpp v149, v149, v149 row_mirror row_mask:0xf bank_mask:0xf bound_ctrl:1
	v_pk_fma_f32 v[100:101], v[148:149], v[136:137], v[100:101] op_sel_hi:[1,0,1]
	v_pk_fma_f32 v[102:103], v[148:149], v[136:137], v[102:103] op_sel:[0,1,0]
	v_pk_fma_f32 v[104:105], v[148:149], v[138:139], v[104:105] op_sel_hi:[1,0,1]
	v_pk_fma_f32 v[106:107], v[148:149], v[138:139], v[106:107] op_sel:[0,1,0]
	s_waitcnt lgkmcnt(0)
	ds_read_b128 v[128:131], v156 offset:48384
	ds_read_b128 v[132:135], v156 offset:48640
	ds_read_b128 v[140:143], v156 offset:49408
	ds_read_b128 v[144:147], v157 offset:48384
	ds_read_b128 v[136:139], v156 offset:49152
	v_pk_mul_f32 v[148:149], v[100:101], v[108:109] op_sel_hi:[1,0]
	v_pk_mul_f32 v[150:151], v[100:101], v[112:113] op_sel_hi:[1,0]
	v_pk_fma_f32 v[148:149], v[102:103], v[108:109], v[148:149] op_sel:[0,1,0]
	v_pk_fma_f32 v[150:151], v[102:103], v[112:113], v[150:151] op_sel:[0,1,0]
	v_pk_fma_f32 v[148:149], v[104:105], v[110:111], v[148:149] op_sel_hi:[1,0,1]
	v_pk_fma_f32 v[150:151], v[104:105], v[114:115], v[150:151] op_sel_hi:[1,0,1]
	v_pk_fma_f32 v[148:149], v[106:107], v[110:111], v[148:149] op_sel:[0,1,0]
	v_pk_fma_f32 v[150:151], v[106:107], v[114:115], v[150:151] op_sel:[0,1,0]
	v_pk_fma_f32 v[100:101], v[124:125], v[120:121], v[100:101] op_sel_hi:[1,0,1]
	v_add_f32_dpp v148, v148, v148 quad_perm:[1,0,3,2] row_mask:0xf bank_mask:0xf bound_ctrl:1
	v_add_f32_dpp v149, v149, v149 quad_perm:[1,0,3,2] row_mask:0xf bank_mask:0xf bound_ctrl:1
	v_pk_fma_f32 v[102:103], v[124:125], v[120:121], v[102:103] op_sel:[0,1,0]
	v_pk_fma_f32 v[234:235], v[124:125], v[126:127], v[150:151] op_sel_hi:[1,0,1]
	v_add_f32_dpp v148, v148, v148 quad_perm:[2,3,0,1] row_mask:0xf bank_mask:0xf bound_ctrl:1
	v_add_f32_dpp v149, v149, v149 quad_perm:[2,3,0,1] row_mask:0xf bank_mask:0xf bound_ctrl:1
	v_pk_fma_f32 v[104:105], v[124:125], v[122:123], v[104:105] op_sel_hi:[1,0,1]
	v_pk_fma_f32 v[106:107], v[124:125], v[122:123], v[106:107] op_sel:[0,1,0]
	v_add_f32_dpp v148, v148, v148 row_half_mirror row_mask:0xf bank_mask:0xf bound_ctrl:1
	v_add_f32_dpp v149, v149, v149 row_half_mirror row_mask:0xf bank_mask:0xf bound_ctrl:1
	s_nop 1
	v_add_f32_dpp v148, v148, v148 row_mirror row_mask:0xf bank_mask:0xf bound_ctrl:1
	v_add_f32_dpp v149, v149, v149 row_mirror row_mask:0xf bank_mask:0xf bound_ctrl:1
	v_pk_fma_f32 v[100:101], v[148:149], v[116:117], v[100:101] op_sel_hi:[1,0,1]
	v_pk_fma_f32 v[102:103], v[148:149], v[116:117], v[102:103] op_sel:[0,1,0]
	v_pk_fma_f32 v[104:105], v[148:149], v[118:119], v[104:105] op_sel_hi:[1,0,1]
	v_pk_fma_f32 v[106:107], v[148:149], v[118:119], v[106:107] op_sel:[0,1,0]
	s_waitcnt lgkmcnt(0)
	ds_read_b128 v[108:111], v156 offset:50176
	ds_read_b128 v[112:115], v156 offset:50432
	ds_read_b128 v[120:123], v156 offset:51200
	ds_read_b128 v[124:127], v157 offset:50176
	ds_read_b128 v[116:119], v156 offset:50944
	v_pk_mul_f32 v[148:149], v[100:101], v[128:129] op_sel_hi:[1,0]
	v_pk_mul_f32 v[150:151], v[100:101], v[132:133] op_sel_hi:[1,0]
	v_pk_fma_f32 v[148:149], v[102:103], v[128:129], v[148:149] op_sel:[0,1,0]
	v_pk_fma_f32 v[150:151], v[102:103], v[132:133], v[150:151] op_sel:[0,1,0]
	v_pk_fma_f32 v[148:149], v[104:105], v[130:131], v[148:149] op_sel_hi:[1,0,1]
	v_pk_fma_f32 v[150:151], v[104:105], v[134:135], v[150:151] op_sel_hi:[1,0,1]
	v_pk_fma_f32 v[148:149], v[106:107], v[130:131], v[148:149] op_sel:[0,1,0]
	v_pk_fma_f32 v[150:151], v[106:107], v[134:135], v[150:151] op_sel:[0,1,0]
	v_pk_fma_f32 v[100:101], v[144:145], v[140:141], v[100:101] op_sel_hi:[1,0,1]
	v_add_f32_dpp v148, v148, v148 quad_perm:[1,0,3,2] row_mask:0xf bank_mask:0xf bound_ctrl:1
	v_add_f32_dpp v149, v149, v149 quad_perm:[1,0,3,2] row_mask:0xf bank_mask:0xf bound_ctrl:1
	v_pk_fma_f32 v[102:103], v[144:145], v[140:141], v[102:103] op_sel:[0,1,0]
	v_pk_fma_f32 v[236:237], v[144:145], v[146:147], v[150:151] op_sel_hi:[1,0,1]
	v_add_f32_dpp v148, v148, v148 quad_perm:[2,3,0,1] row_mask:0xf bank_mask:0xf bound_ctrl:1
	v_add_f32_dpp v149, v149, v149 quad_perm:[2,3,0,1] row_mask:0xf bank_mask:0xf bound_ctrl:1
	v_pk_fma_f32 v[104:105], v[144:145], v[142:143], v[104:105] op_sel_hi:[1,0,1]
	v_pk_fma_f32 v[106:107], v[144:145], v[142:143], v[106:107] op_sel:[0,1,0]
	v_add_f32_dpp v148, v148, v148 row_half_mirror row_mask:0xf bank_mask:0xf bound_ctrl:1
	v_add_f32_dpp v149, v149, v149 row_half_mirror row_mask:0xf bank_mask:0xf bound_ctrl:1
	s_nop 1
	v_add_f32_dpp v148, v148, v148 row_mirror row_mask:0xf bank_mask:0xf bound_ctrl:1
	v_add_f32_dpp v149, v149, v149 row_mirror row_mask:0xf bank_mask:0xf bound_ctrl:1
	v_pk_fma_f32 v[100:101], v[148:149], v[136:137], v[100:101] op_sel_hi:[1,0,1]
	v_pk_fma_f32 v[102:103], v[148:149], v[136:137], v[102:103] op_sel:[0,1,0]
	v_pk_fma_f32 v[104:105], v[148:149], v[138:139], v[104:105] op_sel_hi:[1,0,1]
	v_pk_fma_f32 v[106:107], v[148:149], v[138:139], v[106:107] op_sel:[0,1,0]
	s_waitcnt lgkmcnt(0)
	ds_read_b128 v[128:131], v156 offset:51968
	ds_read_b128 v[132:135], v156 offset:52224
	ds_read_b128 v[140:143], v156 offset:52992
	ds_read_b128 v[144:147], v157 offset:51968
	ds_read_b128 v[136:139], v156 offset:52736
	v_pk_mul_f32 v[148:149], v[100:101], v[108:109] op_sel_hi:[1,0]
	v_pk_mul_f32 v[150:151], v[100:101], v[112:113] op_sel_hi:[1,0]
	v_pk_fma_f32 v[148:149], v[102:103], v[108:109], v[148:149] op_sel:[0,1,0]
	v_pk_fma_f32 v[150:151], v[102:103], v[112:113], v[150:151] op_sel:[0,1,0]
	v_pk_fma_f32 v[148:149], v[104:105], v[110:111], v[148:149] op_sel_hi:[1,0,1]
	v_pk_fma_f32 v[150:151], v[104:105], v[114:115], v[150:151] op_sel_hi:[1,0,1]
	v_pk_fma_f32 v[148:149], v[106:107], v[110:111], v[148:149] op_sel:[0,1,0]
	v_pk_fma_f32 v[150:151], v[106:107], v[114:115], v[150:151] op_sel:[0,1,0]
	v_pk_fma_f32 v[100:101], v[124:125], v[120:121], v[100:101] op_sel_hi:[1,0,1]
	v_add_f32_dpp v148, v148, v148 quad_perm:[1,0,3,2] row_mask:0xf bank_mask:0xf bound_ctrl:1
	v_add_f32_dpp v149, v149, v149 quad_perm:[1,0,3,2] row_mask:0xf bank_mask:0xf bound_ctrl:1
	v_pk_fma_f32 v[102:103], v[124:125], v[120:121], v[102:103] op_sel:[0,1,0]
	v_pk_fma_f32 v[238:239], v[124:125], v[126:127], v[150:151] op_sel_hi:[1,0,1]
	v_add_f32_dpp v148, v148, v148 quad_perm:[2,3,0,1] row_mask:0xf bank_mask:0xf bound_ctrl:1
	v_add_f32_dpp v149, v149, v149 quad_perm:[2,3,0,1] row_mask:0xf bank_mask:0xf bound_ctrl:1
	v_pk_fma_f32 v[104:105], v[124:125], v[122:123], v[104:105] op_sel_hi:[1,0,1]
	v_pk_fma_f32 v[106:107], v[124:125], v[122:123], v[106:107] op_sel:[0,1,0]
	v_add_f32_dpp v148, v148, v148 row_half_mirror row_mask:0xf bank_mask:0xf bound_ctrl:1
	v_add_f32_dpp v149, v149, v149 row_half_mirror row_mask:0xf bank_mask:0xf bound_ctrl:1
	s_nop 1
	v_add_f32_dpp v148, v148, v148 row_mirror row_mask:0xf bank_mask:0xf bound_ctrl:1
	v_add_f32_dpp v149, v149, v149 row_mirror row_mask:0xf bank_mask:0xf bound_ctrl:1
	v_pk_fma_f32 v[100:101], v[148:149], v[116:117], v[100:101] op_sel_hi:[1,0,1]
	v_pk_fma_f32 v[102:103], v[148:149], v[116:117], v[102:103] op_sel:[0,1,0]
	v_pk_fma_f32 v[104:105], v[148:149], v[118:119], v[104:105] op_sel_hi:[1,0,1]
	v_pk_fma_f32 v[106:107], v[148:149], v[118:119], v[106:107] op_sel:[0,1,0]
	s_waitcnt lgkmcnt(0)
	ds_read_b128 v[108:111], v156 offset:53760
	ds_read_b128 v[112:115], v156 offset:54016
	ds_read_b128 v[120:123], v156 offset:54784
	ds_read_b128 v[124:127], v157 offset:53760
	ds_read_b128 v[116:119], v156 offset:54528
	v_pk_mul_f32 v[148:149], v[100:101], v[128:129] op_sel_hi:[1,0]
	v_pk_mul_f32 v[150:151], v[100:101], v[132:133] op_sel_hi:[1,0]
	v_pk_fma_f32 v[148:149], v[102:103], v[128:129], v[148:149] op_sel:[0,1,0]
	v_pk_fma_f32 v[150:151], v[102:103], v[132:133], v[150:151] op_sel:[0,1,0]
	v_pk_fma_f32 v[148:149], v[104:105], v[130:131], v[148:149] op_sel_hi:[1,0,1]
	v_pk_fma_f32 v[150:151], v[104:105], v[134:135], v[150:151] op_sel_hi:[1,0,1]
	v_pk_fma_f32 v[148:149], v[106:107], v[130:131], v[148:149] op_sel:[0,1,0]
	v_pk_fma_f32 v[150:151], v[106:107], v[134:135], v[150:151] op_sel:[0,1,0]
	v_pk_fma_f32 v[100:101], v[144:145], v[140:141], v[100:101] op_sel_hi:[1,0,1]
	v_add_f32_dpp v148, v148, v148 quad_perm:[1,0,3,2] row_mask:0xf bank_mask:0xf bound_ctrl:1
	v_add_f32_dpp v149, v149, v149 quad_perm:[1,0,3,2] row_mask:0xf bank_mask:0xf bound_ctrl:1
	v_pk_fma_f32 v[102:103], v[144:145], v[140:141], v[102:103] op_sel:[0,1,0]
	v_pk_fma_f32 v[240:241], v[144:145], v[146:147], v[150:151] op_sel_hi:[1,0,1]
	v_add_f32_dpp v148, v148, v148 quad_perm:[2,3,0,1] row_mask:0xf bank_mask:0xf bound_ctrl:1
	v_add_f32_dpp v149, v149, v149 quad_perm:[2,3,0,1] row_mask:0xf bank_mask:0xf bound_ctrl:1
	v_pk_fma_f32 v[104:105], v[144:145], v[142:143], v[104:105] op_sel_hi:[1,0,1]
	v_pk_fma_f32 v[106:107], v[144:145], v[142:143], v[106:107] op_sel:[0,1,0]
	v_add_f32_dpp v148, v148, v148 row_half_mirror row_mask:0xf bank_mask:0xf bound_ctrl:1
	v_add_f32_dpp v149, v149, v149 row_half_mirror row_mask:0xf bank_mask:0xf bound_ctrl:1
	s_nop 1
	v_add_f32_dpp v148, v148, v148 row_mirror row_mask:0xf bank_mask:0xf bound_ctrl:1
	v_add_f32_dpp v149, v149, v149 row_mirror row_mask:0xf bank_mask:0xf bound_ctrl:1
	v_pk_fma_f32 v[100:101], v[148:149], v[136:137], v[100:101] op_sel_hi:[1,0,1]
	v_pk_fma_f32 v[102:103], v[148:149], v[136:137], v[102:103] op_sel:[0,1,0]
	v_pk_fma_f32 v[104:105], v[148:149], v[138:139], v[104:105] op_sel_hi:[1,0,1]
	v_pk_fma_f32 v[106:107], v[148:149], v[138:139], v[106:107] op_sel:[0,1,0]
	s_waitcnt lgkmcnt(0)
	ds_read_b128 v[128:131], v156 offset:55552
	ds_read_b128 v[132:135], v156 offset:55808
	ds_read_b128 v[140:143], v156 offset:56576
	ds_read_b128 v[144:147], v157 offset:55552
	ds_read_b128 v[136:139], v156 offset:56320
	v_pk_mul_f32 v[148:149], v[100:101], v[108:109] op_sel_hi:[1,0]
	v_pk_mul_f32 v[150:151], v[100:101], v[112:113] op_sel_hi:[1,0]
	v_pk_fma_f32 v[148:149], v[102:103], v[108:109], v[148:149] op_sel:[0,1,0]
	v_pk_fma_f32 v[150:151], v[102:103], v[112:113], v[150:151] op_sel:[0,1,0]
	v_pk_fma_f32 v[148:149], v[104:105], v[110:111], v[148:149] op_sel_hi:[1,0,1]
	v_pk_fma_f32 v[150:151], v[104:105], v[114:115], v[150:151] op_sel_hi:[1,0,1]
	v_pk_fma_f32 v[148:149], v[106:107], v[110:111], v[148:149] op_sel:[0,1,0]
	v_pk_fma_f32 v[150:151], v[106:107], v[114:115], v[150:151] op_sel:[0,1,0]
	v_pk_fma_f32 v[100:101], v[124:125], v[120:121], v[100:101] op_sel_hi:[1,0,1]
	v_add_f32_dpp v148, v148, v148 quad_perm:[1,0,3,2] row_mask:0xf bank_mask:0xf bound_ctrl:1
	v_add_f32_dpp v149, v149, v149 quad_perm:[1,0,3,2] row_mask:0xf bank_mask:0xf bound_ctrl:1
	v_pk_fma_f32 v[102:103], v[124:125], v[120:121], v[102:103] op_sel:[0,1,0]
	v_pk_fma_f32 v[242:243], v[124:125], v[126:127], v[150:151] op_sel_hi:[1,0,1]
	v_add_f32_dpp v148, v148, v148 quad_perm:[2,3,0,1] row_mask:0xf bank_mask:0xf bound_ctrl:1
	v_add_f32_dpp v149, v149, v149 quad_perm:[2,3,0,1] row_mask:0xf bank_mask:0xf bound_ctrl:1
	v_pk_fma_f32 v[104:105], v[124:125], v[122:123], v[104:105] op_sel_hi:[1,0,1]
	v_pk_fma_f32 v[106:107], v[124:125], v[122:123], v[106:107] op_sel:[0,1,0]
	v_add_f32_dpp v148, v148, v148 row_half_mirror row_mask:0xf bank_mask:0xf bound_ctrl:1
	v_add_f32_dpp v149, v149, v149 row_half_mirror row_mask:0xf bank_mask:0xf bound_ctrl:1
	s_nop 1
	v_add_f32_dpp v148, v148, v148 row_mirror row_mask:0xf bank_mask:0xf bound_ctrl:1
	v_add_f32_dpp v149, v149, v149 row_mirror row_mask:0xf bank_mask:0xf bound_ctrl:1
	v_pk_fma_f32 v[100:101], v[148:149], v[116:117], v[100:101] op_sel_hi:[1,0,1]
	v_pk_fma_f32 v[102:103], v[148:149], v[116:117], v[102:103] op_sel:[0,1,0]
	v_pk_fma_f32 v[104:105], v[148:149], v[118:119], v[104:105] op_sel_hi:[1,0,1]
	v_pk_fma_f32 v[106:107], v[148:149], v[118:119], v[106:107] op_sel:[0,1,0]
	s_waitcnt lgkmcnt(0)
	ds_read_b128 v[204:207], v156 offset:56064
	s_nop 0
	v_pk_mul_f32 v[148:149], v[100:101], v[128:129] op_sel_hi:[1,0]
	v_pk_mul_f32 v[150:151], v[100:101], v[132:133] op_sel_hi:[1,0]
	v_pk_fma_f32 v[148:149], v[102:103], v[128:129], v[148:149] op_sel:[0,1,0]
	v_pk_fma_f32 v[150:151], v[102:103], v[132:133], v[150:151] op_sel:[0,1,0]
	v_pk_fma_f32 v[148:149], v[104:105], v[130:131], v[148:149] op_sel_hi:[1,0,1]
	v_pk_fma_f32 v[150:151], v[104:105], v[134:135], v[150:151] op_sel_hi:[1,0,1]
	v_pk_fma_f32 v[148:149], v[106:107], v[130:131], v[148:149] op_sel:[0,1,0]
	v_pk_fma_f32 v[150:151], v[106:107], v[134:135], v[150:151] op_sel:[0,1,0]
	v_pk_fma_f32 v[100:101], v[144:145], v[140:141], v[100:101] op_sel_hi:[1,0,1]
	v_add_f32_dpp v148, v148, v148 quad_perm:[1,0,3,2] row_mask:0xf bank_mask:0xf bound_ctrl:1
	v_add_f32_dpp v149, v149, v149 quad_perm:[1,0,3,2] row_mask:0xf bank_mask:0xf bound_ctrl:1
	v_pk_fma_f32 v[102:103], v[144:145], v[140:141], v[102:103] op_sel:[0,1,0]
	v_pk_fma_f32 v[244:245], v[144:145], v[146:147], v[150:151] op_sel_hi:[1,0,1]
	v_add_f32_dpp v148, v148, v148 quad_perm:[2,3,0,1] row_mask:0xf bank_mask:0xf bound_ctrl:1
	v_add_f32_dpp v149, v149, v149 quad_perm:[2,3,0,1] row_mask:0xf bank_mask:0xf bound_ctrl:1
	v_pk_fma_f32 v[104:105], v[144:145], v[142:143], v[104:105] op_sel_hi:[1,0,1]
	v_pk_fma_f32 v[106:107], v[144:145], v[142:143], v[106:107] op_sel:[0,1,0]
	v_add_f32_dpp v148, v148, v148 row_half_mirror row_mask:0xf bank_mask:0xf bound_ctrl:1
	v_add_f32_dpp v149, v149, v149 row_half_mirror row_mask:0xf bank_mask:0xf bound_ctrl:1
	s_nop 1
	v_add_f32_dpp v148, v148, v148 row_mirror row_mask:0xf bank_mask:0xf bound_ctrl:1
	v_add_f32_dpp v149, v149, v149 row_mirror row_mask:0xf bank_mask:0xf bound_ctrl:1
	v_pk_fma_f32 v[100:101], v[148:149], v[136:137], v[100:101] op_sel_hi:[1,0,1]
	v_pk_fma_f32 v[102:103], v[148:149], v[136:137], v[102:103] op_sel:[0,1,0]
	v_pk_fma_f32 v[104:105], v[148:149], v[138:139], v[104:105] op_sel_hi:[1,0,1]
	v_pk_fma_f32 v[106:107], v[148:149], v[138:139], v[106:107] op_sel:[0,1,0]
	v_add_f32_dpp v212, v212, v212 row_mirror row_mask:0xf bank_mask:0x3
	v_add_f32_dpp v213, v213, v213 row_mirror row_mask:0xf bank_mask:0x3
	v_add_f32_dpp v212, v228, v228 row_mirror row_mask:0xf bank_mask:0xc
	v_add_f32_dpp v213, v229, v229 row_mirror row_mask:0xf bank_mask:0xc
	v_add_f32_dpp v214, v214, v214 row_mirror row_mask:0xf bank_mask:0x3
	v_add_f32_dpp v215, v215, v215 row_mirror row_mask:0xf bank_mask:0x3
	v_add_f32_dpp v214, v230, v230 row_mirror row_mask:0xf bank_mask:0xc
	v_add_f32_dpp v215, v231, v231 row_mirror row_mask:0xf bank_mask:0xc
	v_add_f32_dpp v216, v216, v216 row_mirror row_mask:0xf bank_mask:0x3
	v_add_f32_dpp v217, v217, v217 row_mirror row_mask:0xf bank_mask:0x3
	v_add_f32_dpp v216, v234, v234 row_mirror row_mask:0xf bank_mask:0xc
	v_add_f32_dpp v217, v235, v235 row_mirror row_mask:0xf bank_mask:0xc
	v_add_f32_dpp v218, v218, v218 row_mirror row_mask:0xf bank_mask:0x3
	v_add_f32_dpp v219, v219, v219 row_mirror row_mask:0xf bank_mask:0x3
	v_add_f32_dpp v218, v236, v236 row_mirror row_mask:0xf bank_mask:0xc
	v_add_f32_dpp v219, v237, v237 row_mirror row_mask:0xf bank_mask:0xc
	v_add_f32_dpp v220, v220, v220 row_mirror row_mask:0xf bank_mask:0x3
	v_add_f32_dpp v221, v221, v221 row_mirror row_mask:0xf bank_mask:0x3
	v_add_f32_dpp v220, v238, v238 row_mirror row_mask:0xf bank_mask:0xc
	v_add_f32_dpp v221, v239, v239 row_mirror row_mask:0xf bank_mask:0xc
	v_add_f32_dpp v222, v222, v222 row_mirror row_mask:0xf bank_mask:0x3
	v_add_f32_dpp v223, v223, v223 row_mirror row_mask:0xf bank_mask:0x3
	v_add_f32_dpp v222, v240, v240 row_mirror row_mask:0xf bank_mask:0xc
	v_add_f32_dpp v223, v241, v241 row_mirror row_mask:0xf bank_mask:0xc
	v_add_f32_dpp v224, v224, v224 row_mirror row_mask:0xf bank_mask:0x3
	v_add_f32_dpp v225, v225, v225 row_mirror row_mask:0xf bank_mask:0x3
	v_add_f32_dpp v224, v242, v242 row_mirror row_mask:0xf bank_mask:0xc
	v_add_f32_dpp v225, v243, v243 row_mirror row_mask:0xf bank_mask:0xc
	v_add_f32_dpp v226, v226, v226 row_mirror row_mask:0xf bank_mask:0x3
	v_add_f32_dpp v227, v227, v227 row_mirror row_mask:0xf bank_mask:0x3
	v_add_f32_dpp v226, v244, v244 row_mirror row_mask:0xf bank_mask:0xc
	v_add_f32_dpp v227, v245, v245 row_mirror row_mask:0xf bank_mask:0xc
	v_add_f32_dpp v212, v212, v212 row_half_mirror row_mask:0xf bank_mask:0x5
	v_add_f32_dpp v213, v213, v213 row_half_mirror row_mask:0xf bank_mask:0x5
	v_add_f32_dpp v212, v220, v220 row_half_mirror row_mask:0xf bank_mask:0xa
	v_add_f32_dpp v213, v221, v221 row_half_mirror row_mask:0xf bank_mask:0xa
	v_add_f32_dpp v214, v214, v214 row_half_mirror row_mask:0xf bank_mask:0x5
	v_add_f32_dpp v215, v215, v215 row_half_mirror row_mask:0xf bank_mask:0x5
	v_add_f32_dpp v214, v222, v222 row_half_mirror row_mask:0xf bank_mask:0xa
	v_add_f32_dpp v215, v223, v223 row_half_mirror row_mask:0xf bank_mask:0xa
	v_add_f32_dpp v216, v216, v216 row_half_mirror row_mask:0xf bank_mask:0x5
	v_add_f32_dpp v217, v217, v217 row_half_mirror row_mask:0xf bank_mask:0x5
	v_add_f32_dpp v216, v224, v224 row_half_mirror row_mask:0xf bank_mask:0xa
	v_add_f32_dpp v217, v225, v225 row_half_mirror row_mask:0xf bank_mask:0xa
	v_add_f32_dpp v218, v218, v218 row_half_mirror row_mask:0xf bank_mask:0x5
	v_add_f32_dpp v219, v219, v219 row_half_mirror row_mask:0xf bank_mask:0x5
	v_add_f32_dpp v218, v226, v226 row_half_mirror row_mask:0xf bank_mask:0xa
	v_add_f32_dpp v219, v227, v227 row_half_mirror row_mask:0xf bank_mask:0xa
	v_add_f32_dpp v212, v212, v212 quad_perm:[1,0,3,2] row_mask:0xf bank_mask:0xf
	v_add_f32_dpp v213, v213, v213 quad_perm:[1,0,3,2] row_mask:0xf bank_mask:0xf
	v_add_f32_dpp v214, v214, v214 quad_perm:[1,0,3,2] row_mask:0xf bank_mask:0xf
	v_add_f32_dpp v215, v215, v215 quad_perm:[1,0,3,2] row_mask:0xf bank_mask:0xf
	v_add_f32_dpp v216, v216, v216 quad_perm:[1,0,3,2] row_mask:0xf bank_mask:0xf
	v_add_f32_dpp v217, v217, v217 quad_perm:[1,0,3,2] row_mask:0xf bank_mask:0xf
	v_add_f32_dpp v218, v218, v218 quad_perm:[1,0,3,2] row_mask:0xf bank_mask:0xf
	v_add_f32_dpp v219, v219, v219 quad_perm:[1,0,3,2] row_mask:0xf bank_mask:0xf
	v_add_f32_dpp v212, v212, v212 quad_perm:[2,3,0,1] row_mask:0xf bank_mask:0xf
	v_add_f32_dpp v213, v213, v213 quad_perm:[2,3,0,1] row_mask:0xf bank_mask:0xf
	v_add_f32_dpp v214, v214, v214 quad_perm:[2,3,0,1] row_mask:0xf bank_mask:0xf
	v_add_f32_dpp v215, v215, v215 quad_perm:[2,3,0,1] row_mask:0xf bank_mask:0xf
	v_add_f32_dpp v216, v216, v216 quad_perm:[2,3,0,1] row_mask:0xf bank_mask:0xf
	v_add_f32_dpp v217, v217, v217 quad_perm:[2,3,0,1] row_mask:0xf bank_mask:0xf
	v_add_f32_dpp v218, v218, v218 quad_perm:[2,3,0,1] row_mask:0xf bank_mask:0xf
	v_add_f32_dpp v219, v219, v219 quad_perm:[2,3,0,1] row_mask:0xf bank_mask:0xf
	v_cndmask_b32_e64 v212, v212, v214, s[52:53]
	v_cndmask_b32_e64 v213, v213, v215, s[52:53]
	v_cndmask_b32_e64 v212, v212, v216, s[54:55]
	v_cndmask_b32_e64 v213, v213, v217, s[54:55]
	v_cndmask_b32_e64 v212, v212, v218, vcc
	v_cndmask_b32_e64 v213, v213, v219, vcc
	v_cvt_pk_bf16_f32 v155, v212, v213
	global_store_dword v[160:161], v155, off
	s_waitcnt lgkmcnt(0)
	v_pk_mul_f32 v[100:101], v[100:101], v[204:205] op_sel_hi:[1,0]
	v_pk_mul_f32 v[102:103], v[102:103], v[204:205] op_sel:[0,1]
	v_pk_mul_f32 v[104:105], v[104:105], v[206:207] op_sel_hi:[1,0]
	v_pk_mul_f32 v[106:107], v[106:107], v[206:207] op_sel:[0,1]
	s_cmp_lg_u32 s30, 63
	s_cbranch_scc1 .Lrwp_done
	v_mov_b32_e32 v14, v100
	v_mov_b32_e32 v15, v102
	v_mov_b32_e32 v16, v104
	v_mov_b32_e32 v17, v106
	v_mov_b32_e32 v10, v101
	v_mov_b32_e32 v11, v103
	v_mov_b32_e32 v12, v105
	v_mov_b32_e32 v13, v107
